# v44: GTR straight-line + ML1 load reorder + 8 row-norm phases chained behind their residual GEMM by per-row-panel counters (grid barrier between GEMM and norm dropped)
# speedup vs baseline: 1.0432x; 1.0145x over previous
.LBB0_119:
	s_ashr_i32 s7, s6, 31
	s_lshl_b64 s[8:9], s[6:7], 11
	v_lshl_add_u64 v[8:9], v[6:7], 0, s[8:9]
	s_mov_b64 s[8:9], 0
	v_mov_b32_e32 v10, v50
	v_add_co_u32_e32 v80, vcc, 0xe800000, v8
	s_nop 1
	v_addc_co_u32_e32 v81, vcc, 0, v9, vcc
	global_load_dwordx2 v[84:85], v[80:81], off
	global_load_dwordx2 v[86:87], v[80:81], off offset:512
	global_load_dwordx2 v[88:89], v[80:81], off offset:1024
	global_load_dwordx2 v[90:91], v[80:81], off offset:1536
	global_load_dwordx2 v[92:93], v[80:81], off offset:2048
	global_load_dwordx2 v[94:95], v[80:81], off offset:2560
	global_load_dwordx2 v[96:97], v[80:81], off offset:3072
	global_load_dwordx2 v[98:99], v[80:81], off offset:3584
	v_add_co_u32_e32 v80, vcc, 0x1000, v80
	s_nop 1
	v_addc_co_u32_e32 v81, vcc, 0, v81, vcc
	global_load_dwordx2 v[100:101], v[80:81], off
	global_load_dwordx2 v[102:103], v[80:81], off offset:512
	global_load_dwordx2 v[104:105], v[80:81], off offset:1024
	global_load_dwordx2 v[106:107], v[80:81], off offset:1536
	global_load_dwordx2 v[108:109], v[80:81], off offset:2048
	global_load_dwordx2 v[110:111], v[80:81], off offset:2560
	global_load_dwordx2 v[112:113], v[80:81], off offset:3072
	global_load_dwordx2 v[114:115], v[80:81], off offset:3584
	v_add_co_u32_e32 v80, vcc, 0x1000, v80
	s_nop 1
	v_addc_co_u32_e32 v81, vcc, 0, v81, vcc
	global_load_dwordx2 v[116:117], v[80:81], off
	global_load_dwordx2 v[118:119], v[80:81], off offset:512
	global_load_dwordx2 v[120:121], v[80:81], off offset:1024
	global_load_dwordx2 v[122:123], v[80:81], off offset:1536
	global_load_dwordx2 v[124:125], v[80:81], off offset:2048
	global_load_dwordx2 v[126:127], v[80:81], off offset:2560
	global_load_dwordx2 v[128:129], v[80:81], off offset:3072
	global_load_dwordx2 v[130:131], v[80:81], off offset:3584
	v_add_co_u32_e32 v80, vcc, 0x1000, v80
	s_nop 1
	v_addc_co_u32_e32 v81, vcc, 0, v81, vcc
	global_load_dwordx2 v[132:133], v[80:81], off
	global_load_dwordx2 v[134:135], v[80:81], off offset:512
	global_load_dwordx2 v[136:137], v[80:81], off offset:1024
	global_load_dwordx2 v[138:139], v[80:81], off offset:1536
	global_load_dwordx2 v[140:141], v[80:81], off offset:2048
	global_load_dwordx2 v[142:143], v[80:81], off offset:2560
	global_load_dwordx2 v[144:145], v[80:81], off offset:3072
	global_load_dwordx2 v[146:147], v[80:81], off offset:3584
	s_mov_b32 s8, 0x3a800000
	s_waitcnt vmcnt(28)
	v_lshlrev_b32_e32 v82, 16, v84
	v_and_b32_e32 v83, 0xffff0000, v84
	v_mul_f32_e32 v148, v82, v82
	v_fmac_f32_e32 v148, v83, v83
	v_lshlrev_b32_e32 v82, 16, v85
	v_and_b32_e32 v83, 0xffff0000, v85
	v_fmac_f32_e32 v148, v82, v82
	v_fmac_f32_e32 v148, v83, v83
	v_lshlrev_b32_e32 v82, 16, v86
	v_and_b32_e32 v83, 0xffff0000, v86
	v_fmac_f32_e32 v148, v82, v82
	v_fmac_f32_e32 v148, v83, v83
	v_lshlrev_b32_e32 v82, 16, v87
	v_and_b32_e32 v83, 0xffff0000, v87
	v_fmac_f32_e32 v148, v82, v82
	v_fmac_f32_e32 v148, v83, v83
	v_lshlrev_b32_e32 v82, 16, v88
	v_and_b32_e32 v83, 0xffff0000, v88
	v_fmac_f32_e32 v148, v82, v82
	v_fmac_f32_e32 v148, v83, v83
	v_lshlrev_b32_e32 v82, 16, v89
	v_and_b32_e32 v83, 0xffff0000, v89
	v_fmac_f32_e32 v148, v82, v82
	v_fmac_f32_e32 v148, v83, v83
	v_lshlrev_b32_e32 v82, 16, v90
	v_and_b32_e32 v83, 0xffff0000, v90
	v_fmac_f32_e32 v148, v82, v82
	v_fmac_f32_e32 v148, v83, v83
	v_lshlrev_b32_e32 v82, 16, v91
	v_and_b32_e32 v83, 0xffff0000, v91
	v_fmac_f32_e32 v148, v82, v82
	v_fmac_f32_e32 v148, v83, v83
	s_waitcnt vmcnt(24)
	v_lshlrev_b32_e32 v82, 16, v92
	v_and_b32_e32 v83, 0xffff0000, v92
	v_mul_f32_e32 v149, v82, v82
	v_fmac_f32_e32 v149, v83, v83
	v_lshlrev_b32_e32 v82, 16, v93
	v_and_b32_e32 v83, 0xffff0000, v93
	v_fmac_f32_e32 v149, v82, v82
	v_fmac_f32_e32 v149, v83, v83
	v_lshlrev_b32_e32 v82, 16, v94
	v_and_b32_e32 v83, 0xffff0000, v94
	v_fmac_f32_e32 v149, v82, v82
	v_fmac_f32_e32 v149, v83, v83
	v_lshlrev_b32_e32 v82, 16, v95
	v_and_b32_e32 v83, 0xffff0000, v95
	v_fmac_f32_e32 v149, v82, v82
	v_fmac_f32_e32 v149, v83, v83
	v_lshlrev_b32_e32 v82, 16, v96
	v_and_b32_e32 v83, 0xffff0000, v96
	v_fmac_f32_e32 v149, v82, v82
	v_fmac_f32_e32 v149, v83, v83
	v_lshlrev_b32_e32 v82, 16, v97
	v_and_b32_e32 v83, 0xffff0000, v97
	v_fmac_f32_e32 v149, v82, v82
	v_fmac_f32_e32 v149, v83, v83
	v_lshlrev_b32_e32 v82, 16, v98
	v_and_b32_e32 v83, 0xffff0000, v98
	v_fmac_f32_e32 v149, v82, v82
	v_fmac_f32_e32 v149, v83, v83
	v_lshlrev_b32_e32 v82, 16, v99
	v_and_b32_e32 v83, 0xffff0000, v99
	v_fmac_f32_e32 v149, v82, v82
	v_fmac_f32_e32 v149, v83, v83
	s_waitcnt vmcnt(20)
	v_lshlrev_b32_e32 v82, 16, v100
	v_and_b32_e32 v83, 0xffff0000, v100
	v_mul_f32_e32 v150, v82, v82
	v_fmac_f32_e32 v150, v83, v83
	v_lshlrev_b32_e32 v82, 16, v101
	v_and_b32_e32 v83, 0xffff0000, v101
	v_fmac_f32_e32 v150, v82, v82
	v_fmac_f32_e32 v150, v83, v83
	v_lshlrev_b32_e32 v82, 16, v102
	v_and_b32_e32 v83, 0xffff0000, v102
	v_fmac_f32_e32 v150, v82, v82
	v_fmac_f32_e32 v150, v83, v83
	v_lshlrev_b32_e32 v82, 16, v103
	v_and_b32_e32 v83, 0xffff0000, v103
	v_fmac_f32_e32 v150, v82, v82
	v_fmac_f32_e32 v150, v83, v83
	v_lshlrev_b32_e32 v82, 16, v104
	v_and_b32_e32 v83, 0xffff0000, v104
	v_fmac_f32_e32 v150, v82, v82
	v_fmac_f32_e32 v150, v83, v83
	v_lshlrev_b32_e32 v82, 16, v105
	v_and_b32_e32 v83, 0xffff0000, v105
	v_fmac_f32_e32 v150, v82, v82
	v_fmac_f32_e32 v150, v83, v83
	v_lshlrev_b32_e32 v82, 16, v106
	v_and_b32_e32 v83, 0xffff0000, v106
	v_fmac_f32_e32 v150, v82, v82
	v_fmac_f32_e32 v150, v83, v83
	v_lshlrev_b32_e32 v82, 16, v107
	v_and_b32_e32 v83, 0xffff0000, v107
	v_fmac_f32_e32 v150, v82, v82
	v_fmac_f32_e32 v150, v83, v83
	s_waitcnt vmcnt(16)
	v_lshlrev_b32_e32 v82, 16, v108
	v_and_b32_e32 v83, 0xffff0000, v108
	v_mul_f32_e32 v151, v82, v82
	v_fmac_f32_e32 v151, v83, v83
	v_lshlrev_b32_e32 v82, 16, v109
	v_and_b32_e32 v83, 0xffff0000, v109
	v_fmac_f32_e32 v151, v82, v82
	v_fmac_f32_e32 v151, v83, v83
	v_lshlrev_b32_e32 v82, 16, v110
	v_and_b32_e32 v83, 0xffff0000, v110
	v_fmac_f32_e32 v151, v82, v82
	v_fmac_f32_e32 v151, v83, v83
	v_lshlrev_b32_e32 v82, 16, v111
	v_and_b32_e32 v83, 0xffff0000, v111
	v_fmac_f32_e32 v151, v82, v82
	v_fmac_f32_e32 v151, v83, v83
	v_lshlrev_b32_e32 v82, 16, v112
	v_and_b32_e32 v83, 0xffff0000, v112
	v_fmac_f32_e32 v151, v82, v82
	v_fmac_f32_e32 v151, v83, v83
	v_lshlrev_b32_e32 v82, 16, v113
	v_and_b32_e32 v83, 0xffff0000, v113
	v_fmac_f32_e32 v151, v82, v82
	v_fmac_f32_e32 v151, v83, v83
	v_lshlrev_b32_e32 v82, 16, v114
	v_and_b32_e32 v83, 0xffff0000, v114
	v_fmac_f32_e32 v151, v82, v82
	v_fmac_f32_e32 v151, v83, v83
	v_lshlrev_b32_e32 v82, 16, v115
	v_and_b32_e32 v83, 0xffff0000, v115
	v_fmac_f32_e32 v151, v82, v82
	v_fmac_f32_e32 v151, v83, v83
	s_waitcnt vmcnt(12)
	v_lshlrev_b32_e32 v82, 16, v116
	v_and_b32_e32 v83, 0xffff0000, v116
	v_mul_f32_e32 v152, v82, v82
	v_fmac_f32_e32 v152, v83, v83
	v_lshlrev_b32_e32 v82, 16, v117
	v_and_b32_e32 v83, 0xffff0000, v117
	v_fmac_f32_e32 v152, v82, v82
	v_fmac_f32_e32 v152, v83, v83
	v_lshlrev_b32_e32 v82, 16, v118
	v_and_b32_e32 v83, 0xffff0000, v118
	v_fmac_f32_e32 v152, v82, v82
	v_fmac_f32_e32 v152, v83, v83
	v_lshlrev_b32_e32 v82, 16, v119
	v_and_b32_e32 v83, 0xffff0000, v119
	v_fmac_f32_e32 v152, v82, v82
	v_fmac_f32_e32 v152, v83, v83
	v_lshlrev_b32_e32 v82, 16, v120
	v_and_b32_e32 v83, 0xffff0000, v120
	v_fmac_f32_e32 v152, v82, v82
	v_fmac_f32_e32 v152, v83, v83
	v_lshlrev_b32_e32 v82, 16, v121
	v_and_b32_e32 v83, 0xffff0000, v121
	v_fmac_f32_e32 v152, v82, v82
	v_fmac_f32_e32 v152, v83, v83
	v_lshlrev_b32_e32 v82, 16, v122
	v_and_b32_e32 v83, 0xffff0000, v122
	v_fmac_f32_e32 v152, v82, v82
	v_fmac_f32_e32 v152, v83, v83
	v_lshlrev_b32_e32 v82, 16, v123
	v_and_b32_e32 v83, 0xffff0000, v123
	v_fmac_f32_e32 v152, v82, v82
	v_fmac_f32_e32 v152, v83, v83
	s_waitcnt vmcnt(8)
	v_lshlrev_b32_e32 v82, 16, v124
	v_and_b32_e32 v83, 0xffff0000, v124
	v_mul_f32_e32 v153, v82, v82
	v_fmac_f32_e32 v153, v83, v83
	v_lshlrev_b32_e32 v82, 16, v125
	v_and_b32_e32 v83, 0xffff0000, v125
	v_fmac_f32_e32 v153, v82, v82
	v_fmac_f32_e32 v153, v83, v83
	v_lshlrev_b32_e32 v82, 16, v126
	v_and_b32_e32 v83, 0xffff0000, v126
	v_fmac_f32_e32 v153, v82, v82
	v_fmac_f32_e32 v153, v83, v83
	v_lshlrev_b32_e32 v82, 16, v127
	v_and_b32_e32 v83, 0xffff0000, v127
	v_fmac_f32_e32 v153, v82, v82
	v_fmac_f32_e32 v153, v83, v83
	v_lshlrev_b32_e32 v82, 16, v128
	v_and_b32_e32 v83, 0xffff0000, v128
	v_fmac_f32_e32 v153, v82, v82
	v_fmac_f32_e32 v153, v83, v83
	v_lshlrev_b32_e32 v82, 16, v129
	v_and_b32_e32 v83, 0xffff0000, v129
	v_fmac_f32_e32 v153, v82, v82
	v_fmac_f32_e32 v153, v83, v83
	v_lshlrev_b32_e32 v82, 16, v130
	v_and_b32_e32 v83, 0xffff0000, v130
	v_fmac_f32_e32 v153, v82, v82
	v_fmac_f32_e32 v153, v83, v83
	v_lshlrev_b32_e32 v82, 16, v131
	v_and_b32_e32 v83, 0xffff0000, v131
	v_fmac_f32_e32 v153, v82, v82
	v_fmac_f32_e32 v153, v83, v83
	s_waitcnt vmcnt(4)
	v_lshlrev_b32_e32 v82, 16, v132
	v_and_b32_e32 v83, 0xffff0000, v132
	v_mul_f32_e32 v154, v82, v82
	v_fmac_f32_e32 v154, v83, v83
	v_lshlrev_b32_e32 v82, 16, v133
	v_and_b32_e32 v83, 0xffff0000, v133
	v_fmac_f32_e32 v154, v82, v82
	v_fmac_f32_e32 v154, v83, v83
	v_lshlrev_b32_e32 v82, 16, v134
	v_and_b32_e32 v83, 0xffff0000, v134
	v_fmac_f32_e32 v154, v82, v82
	v_fmac_f32_e32 v154, v83, v83
	v_lshlrev_b32_e32 v82, 16, v135
	v_and_b32_e32 v83, 0xffff0000, v135
	v_fmac_f32_e32 v154, v82, v82
	v_fmac_f32_e32 v154, v83, v83
	v_lshlrev_b32_e32 v82, 16, v136
	v_and_b32_e32 v83, 0xffff0000, v136
	v_fmac_f32_e32 v154, v82, v82
	v_fmac_f32_e32 v154, v83, v83
	v_lshlrev_b32_e32 v82, 16, v137
	v_and_b32_e32 v83, 0xffff0000, v137
	v_fmac_f32_e32 v154, v82, v82
	v_fmac_f32_e32 v154, v83, v83
	v_lshlrev_b32_e32 v82, 16, v138
	v_and_b32_e32 v83, 0xffff0000, v138
	v_fmac_f32_e32 v154, v82, v82
	v_fmac_f32_e32 v154, v83, v83
	v_lshlrev_b32_e32 v82, 16, v139
	v_and_b32_e32 v83, 0xffff0000, v139
	v_fmac_f32_e32 v154, v82, v82
	v_fmac_f32_e32 v154, v83, v83
	s_waitcnt vmcnt(0)
	v_lshlrev_b32_e32 v82, 16, v140
	v_and_b32_e32 v83, 0xffff0000, v140
	v_mul_f32_e32 v155, v82, v82
	v_fmac_f32_e32 v155, v83, v83
	v_lshlrev_b32_e32 v82, 16, v141
	v_and_b32_e32 v83, 0xffff0000, v141
	v_fmac_f32_e32 v155, v82, v82
	v_fmac_f32_e32 v155, v83, v83
	v_lshlrev_b32_e32 v82, 16, v142
	v_and_b32_e32 v83, 0xffff0000, v142
	v_fmac_f32_e32 v155, v82, v82
	v_fmac_f32_e32 v155, v83, v83
	v_lshlrev_b32_e32 v82, 16, v143
	v_and_b32_e32 v83, 0xffff0000, v143
	v_fmac_f32_e32 v155, v82, v82
	v_fmac_f32_e32 v155, v83, v83
	v_lshlrev_b32_e32 v82, 16, v144
	v_and_b32_e32 v83, 0xffff0000, v144
	v_fmac_f32_e32 v155, v82, v82
	v_fmac_f32_e32 v155, v83, v83
	v_lshlrev_b32_e32 v82, 16, v145
	v_and_b32_e32 v83, 0xffff0000, v145
	v_fmac_f32_e32 v155, v82, v82
	v_fmac_f32_e32 v155, v83, v83
	v_lshlrev_b32_e32 v82, 16, v146
	v_and_b32_e32 v83, 0xffff0000, v146
	v_fmac_f32_e32 v155, v82, v82
	v_fmac_f32_e32 v155, v83, v83
	v_lshlrev_b32_e32 v82, 16, v147
	v_and_b32_e32 v83, 0xffff0000, v147
	v_fmac_f32_e32 v155, v82, v82
	v_fmac_f32_e32 v155, v83, v83
	s_nop 1
	v_add_f32_dpp v148, v148, v148 row_ror:8 row_mask:0xf bank_mask:0xf
	v_add_f32_dpp v149, v149, v149 row_ror:8 row_mask:0xf bank_mask:0xf
	v_add_f32_dpp v150, v150, v150 row_ror:8 row_mask:0xf bank_mask:0xf
	v_add_f32_dpp v151, v151, v151 row_ror:8 row_mask:0xf bank_mask:0xf
	v_add_f32_dpp v152, v152, v152 row_ror:8 row_mask:0xf bank_mask:0xf
	v_add_f32_dpp v153, v153, v153 row_ror:8 row_mask:0xf bank_mask:0xf
	v_add_f32_dpp v154, v154, v154 row_ror:8 row_mask:0xf bank_mask:0xf
	v_add_f32_dpp v155, v155, v155 row_ror:8 row_mask:0xf bank_mask:0xf
	v_add_f32_dpp v148, v148, v148 row_ror:4 row_mask:0xf bank_mask:0xf
	v_add_f32_dpp v149, v149, v149 row_ror:4 row_mask:0xf bank_mask:0xf
	v_add_f32_dpp v150, v150, v150 row_ror:4 row_mask:0xf bank_mask:0xf
	v_add_f32_dpp v151, v151, v151 row_ror:4 row_mask:0xf bank_mask:0xf
	v_add_f32_dpp v152, v152, v152 row_ror:4 row_mask:0xf bank_mask:0xf
	v_add_f32_dpp v153, v153, v153 row_ror:4 row_mask:0xf bank_mask:0xf
	v_add_f32_dpp v154, v154, v154 row_ror:4 row_mask:0xf bank_mask:0xf
	v_add_f32_dpp v155, v155, v155 row_ror:4 row_mask:0xf bank_mask:0xf
	v_add_f32_dpp v148, v148, v148 row_ror:2 row_mask:0xf bank_mask:0xf
	v_add_f32_dpp v149, v149, v149 row_ror:2 row_mask:0xf bank_mask:0xf
	v_add_f32_dpp v150, v150, v150 row_ror:2 row_mask:0xf bank_mask:0xf
	v_add_f32_dpp v151, v151, v151 row_ror:2 row_mask:0xf bank_mask:0xf
	v_add_f32_dpp v152, v152, v152 row_ror:2 row_mask:0xf bank_mask:0xf
	v_add_f32_dpp v153, v153, v153 row_ror:2 row_mask:0xf bank_mask:0xf
	v_add_f32_dpp v154, v154, v154 row_ror:2 row_mask:0xf bank_mask:0xf
	v_add_f32_dpp v155, v155, v155 row_ror:2 row_mask:0xf bank_mask:0xf
	v_add_f32_dpp v148, v148, v148 row_ror:1 row_mask:0xf bank_mask:0xf
	v_add_f32_dpp v149, v149, v149 row_ror:1 row_mask:0xf bank_mask:0xf
	v_add_f32_dpp v150, v150, v150 row_ror:1 row_mask:0xf bank_mask:0xf
	v_add_f32_dpp v151, v151, v151 row_ror:1 row_mask:0xf bank_mask:0xf
	v_add_f32_dpp v152, v152, v152 row_ror:1 row_mask:0xf bank_mask:0xf
	v_add_f32_dpp v153, v153, v153 row_ror:1 row_mask:0xf bank_mask:0xf
	v_add_f32_dpp v154, v154, v154 row_ror:1 row_mask:0xf bank_mask:0xf
	v_add_f32_dpp v155, v155, v155 row_ror:1 row_mask:0xf bank_mask:0xf
	v_mov_b32_e32 v156, v148
	v_mov_b32_e32 v157, v149
	v_mov_b32_e32 v158, v150
	v_mov_b32_e32 v159, v151
	v_mov_b32_e32 v160, v152
	v_mov_b32_e32 v161, v153
	v_mov_b32_e32 v162, v154
	v_mov_b32_e32 v163, v155
	s_nop 1
	v_permlane16_swap_b32_e32 v156, v148
	v_permlane16_swap_b32_e32 v157, v149
	v_permlane16_swap_b32_e32 v158, v150
	v_permlane16_swap_b32_e32 v159, v151
	v_permlane16_swap_b32_e32 v160, v152
	v_permlane16_swap_b32_e32 v161, v153
	v_permlane16_swap_b32_e32 v162, v154
	v_permlane16_swap_b32_e32 v163, v155
	v_add_f32_e32 v148, v148, v156
	v_add_f32_e32 v149, v149, v157
	v_add_f32_e32 v150, v150, v158
	v_add_f32_e32 v151, v151, v159
	v_add_f32_e32 v152, v152, v160
	v_add_f32_e32 v153, v153, v161
	v_add_f32_e32 v154, v154, v162
	v_add_f32_e32 v155, v155, v163
	v_mov_b32_e32 v156, v148
	v_mov_b32_e32 v157, v149
	v_mov_b32_e32 v158, v150
	v_mov_b32_e32 v159, v151
	v_mov_b32_e32 v160, v152
	v_mov_b32_e32 v161, v153
	v_mov_b32_e32 v162, v154
	v_mov_b32_e32 v163, v155
	s_nop 1
	v_permlane32_swap_b32_e32 v156, v148
	v_permlane32_swap_b32_e32 v157, v149
	v_permlane32_swap_b32_e32 v158, v150
	v_permlane32_swap_b32_e32 v159, v151
	v_permlane32_swap_b32_e32 v160, v152
	v_permlane32_swap_b32_e32 v161, v153
	v_permlane32_swap_b32_e32 v162, v154
	v_permlane32_swap_b32_e32 v163, v155
	v_add_f32_e32 v148, v148, v156
	v_add_f32_e32 v149, v149, v157
	v_add_f32_e32 v150, v150, v158
	v_add_f32_e32 v151, v151, v159
	v_add_f32_e32 v152, v152, v160
	v_add_f32_e32 v153, v153, v161
	v_add_f32_e32 v154, v154, v162
	v_add_f32_e32 v155, v155, v163
	v_fma_f32 v148, v148, s8, v167
	v_fma_f32 v149, v149, s8, v167
	v_fma_f32 v150, v150, s8, v167
	v_fma_f32 v151, v151, s8, v167
	v_fma_f32 v152, v152, s8, v167
	v_fma_f32 v153, v153, s8, v167
	v_fma_f32 v154, v154, s8, v167
	v_fma_f32 v155, v155, s8, v167
	v_rsq_f32_e32 v148, v148
	v_rsq_f32_e32 v149, v149
	v_rsq_f32_e32 v150, v150
	v_rsq_f32_e32 v151, v151
	v_rsq_f32_e32 v152, v152
	v_rsq_f32_e32 v153, v153
	v_rsq_f32_e32 v154, v154
	v_rsq_f32_e32 v155, v155
	s_nop 0
	v_lshlrev_b32_e32 v82, 16, v84
	v_and_b32_e32 v83, 0xffff0000, v84
	v_mul_f32_e32 v82, v82, v148
	v_mul_f32_e32 v83, v83, v148
	v_cvt_pk_bf16_f32 v84, v82, v83
	v_lshlrev_b32_e32 v82, 16, v85
	v_and_b32_e32 v83, 0xffff0000, v85
	v_mul_f32_e32 v82, v82, v148
	v_mul_f32_e32 v83, v83, v148
	v_cvt_pk_bf16_f32 v85, v82, v83
	v_lshlrev_b32_e32 v82, 16, v86
	v_and_b32_e32 v83, 0xffff0000, v86
	v_mul_f32_e32 v82, v82, v148
	v_mul_f32_e32 v83, v83, v148
	v_cvt_pk_bf16_f32 v86, v82, v83
	v_lshlrev_b32_e32 v82, 16, v87
	v_and_b32_e32 v83, 0xffff0000, v87
	v_mul_f32_e32 v82, v82, v148
	v_mul_f32_e32 v83, v83, v148
	v_cvt_pk_bf16_f32 v87, v82, v83
	v_lshlrev_b32_e32 v82, 16, v88
	v_and_b32_e32 v83, 0xffff0000, v88
	v_mul_f32_e32 v82, v82, v148
	v_mul_f32_e32 v83, v83, v148
	v_cvt_pk_bf16_f32 v88, v82, v83
	v_lshlrev_b32_e32 v82, 16, v89
	v_and_b32_e32 v83, 0xffff0000, v89
	v_mul_f32_e32 v82, v82, v148
	v_mul_f32_e32 v83, v83, v148
	v_cvt_pk_bf16_f32 v89, v82, v83
	v_lshlrev_b32_e32 v82, 16, v90
	v_and_b32_e32 v83, 0xffff0000, v90
	v_mul_f32_e32 v82, v82, v148
	v_mul_f32_e32 v83, v83, v148
	v_cvt_pk_bf16_f32 v90, v82, v83
	v_lshlrev_b32_e32 v82, 16, v91
	v_and_b32_e32 v83, 0xffff0000, v91
	v_mul_f32_e32 v82, v82, v148
	v_mul_f32_e32 v83, v83, v148
	v_cvt_pk_bf16_f32 v91, v82, v83
	ds_write2st64_b64 v10, v[84:85], v[86:87] offset1:1
	ds_write2st64_b64 v10, v[88:89], v[90:91] offset0:2 offset1:3
	v_add_u32_e32 v10, 0x800, v10
	v_lshlrev_b32_e32 v82, 16, v92
	v_and_b32_e32 v83, 0xffff0000, v92
	v_mul_f32_e32 v82, v82, v149
	v_mul_f32_e32 v83, v83, v149
	v_cvt_pk_bf16_f32 v92, v82, v83
	v_lshlrev_b32_e32 v82, 16, v93
	v_and_b32_e32 v83, 0xffff0000, v93
	v_mul_f32_e32 v82, v82, v149
	v_mul_f32_e32 v83, v83, v149
	v_cvt_pk_bf16_f32 v93, v82, v83
	v_lshlrev_b32_e32 v82, 16, v94
	v_and_b32_e32 v83, 0xffff0000, v94
	v_mul_f32_e32 v82, v82, v149
	v_mul_f32_e32 v83, v83, v149
	v_cvt_pk_bf16_f32 v94, v82, v83
	v_lshlrev_b32_e32 v82, 16, v95
	v_and_b32_e32 v83, 0xffff0000, v95
	v_mul_f32_e32 v82, v82, v149
	v_mul_f32_e32 v83, v83, v149
	v_cvt_pk_bf16_f32 v95, v82, v83
	v_lshlrev_b32_e32 v82, 16, v96
	v_and_b32_e32 v83, 0xffff0000, v96
	v_mul_f32_e32 v82, v82, v149
	v_mul_f32_e32 v83, v83, v149
	v_cvt_pk_bf16_f32 v96, v82, v83
	v_lshlrev_b32_e32 v82, 16, v97
	v_and_b32_e32 v83, 0xffff0000, v97
	v_mul_f32_e32 v82, v82, v149
	v_mul_f32_e32 v83, v83, v149
	v_cvt_pk_bf16_f32 v97, v82, v83
	v_lshlrev_b32_e32 v82, 16, v98
	v_and_b32_e32 v83, 0xffff0000, v98
	v_mul_f32_e32 v82, v82, v149
	v_mul_f32_e32 v83, v83, v149
	v_cvt_pk_bf16_f32 v98, v82, v83
	v_lshlrev_b32_e32 v82, 16, v99
	v_and_b32_e32 v83, 0xffff0000, v99
	v_mul_f32_e32 v82, v82, v149
	v_mul_f32_e32 v83, v83, v149
	v_cvt_pk_bf16_f32 v99, v82, v83
	ds_write2st64_b64 v10, v[92:93], v[94:95] offset1:1
	ds_write2st64_b64 v10, v[96:97], v[98:99] offset0:2 offset1:3
	v_add_u32_e32 v10, 0x800, v10
	v_lshlrev_b32_e32 v82, 16, v100
	v_and_b32_e32 v83, 0xffff0000, v100
	v_mul_f32_e32 v82, v82, v150
	v_mul_f32_e32 v83, v83, v150
	v_cvt_pk_bf16_f32 v100, v82, v83
	v_lshlrev_b32_e32 v82, 16, v101
	v_and_b32_e32 v83, 0xffff0000, v101
	v_mul_f32_e32 v82, v82, v150
	v_mul_f32_e32 v83, v83, v150
	v_cvt_pk_bf16_f32 v101, v82, v83
	v_lshlrev_b32_e32 v82, 16, v102
	v_and_b32_e32 v83, 0xffff0000, v102
	v_mul_f32_e32 v82, v82, v150
	v_mul_f32_e32 v83, v83, v150
	v_cvt_pk_bf16_f32 v102, v82, v83
	v_lshlrev_b32_e32 v82, 16, v103
	v_and_b32_e32 v83, 0xffff0000, v103
	v_mul_f32_e32 v82, v82, v150
	v_mul_f32_e32 v83, v83, v150
	v_cvt_pk_bf16_f32 v103, v82, v83
	v_lshlrev_b32_e32 v82, 16, v104
	v_and_b32_e32 v83, 0xffff0000, v104
	v_mul_f32_e32 v82, v82, v150
	v_mul_f32_e32 v83, v83, v150
	v_cvt_pk_bf16_f32 v104, v82, v83
	v_lshlrev_b32_e32 v82, 16, v105
	v_and_b32_e32 v83, 0xffff0000, v105
	v_mul_f32_e32 v82, v82, v150
	v_mul_f32_e32 v83, v83, v150
	v_cvt_pk_bf16_f32 v105, v82, v83
	v_lshlrev_b32_e32 v82, 16, v106
	v_and_b32_e32 v83, 0xffff0000, v106
	v_mul_f32_e32 v82, v82, v150
	v_mul_f32_e32 v83, v83, v150
	v_cvt_pk_bf16_f32 v106, v82, v83
	v_lshlrev_b32_e32 v82, 16, v107
	v_and_b32_e32 v83, 0xffff0000, v107
	v_mul_f32_e32 v82, v82, v150
	v_mul_f32_e32 v83, v83, v150
	v_cvt_pk_bf16_f32 v107, v82, v83
	ds_write2st64_b64 v10, v[100:101], v[102:103] offset1:1
	ds_write2st64_b64 v10, v[104:105], v[106:107] offset0:2 offset1:3
	v_add_u32_e32 v10, 0x800, v10
	v_lshlrev_b32_e32 v82, 16, v108
	v_and_b32_e32 v83, 0xffff0000, v108
	v_mul_f32_e32 v82, v82, v151
	v_mul_f32_e32 v83, v83, v151
	v_cvt_pk_bf16_f32 v108, v82, v83
	v_lshlrev_b32_e32 v82, 16, v109
	v_and_b32_e32 v83, 0xffff0000, v109
	v_mul_f32_e32 v82, v82, v151
	v_mul_f32_e32 v83, v83, v151
	v_cvt_pk_bf16_f32 v109, v82, v83
	v_lshlrev_b32_e32 v82, 16, v110
	v_and_b32_e32 v83, 0xffff0000, v110
	v_mul_f32_e32 v82, v82, v151
	v_mul_f32_e32 v83, v83, v151
	v_cvt_pk_bf16_f32 v110, v82, v83
	v_lshlrev_b32_e32 v82, 16, v111
	v_and_b32_e32 v83, 0xffff0000, v111
	v_mul_f32_e32 v82, v82, v151
	v_mul_f32_e32 v83, v83, v151
	v_cvt_pk_bf16_f32 v111, v82, v83
	v_lshlrev_b32_e32 v82, 16, v112
	v_and_b32_e32 v83, 0xffff0000, v112
	v_mul_f32_e32 v82, v82, v151
	v_mul_f32_e32 v83, v83, v151
	v_cvt_pk_bf16_f32 v112, v82, v83
	v_lshlrev_b32_e32 v82, 16, v113
	v_and_b32_e32 v83, 0xffff0000, v113
	v_mul_f32_e32 v82, v82, v151
	v_mul_f32_e32 v83, v83, v151
	v_cvt_pk_bf16_f32 v113, v82, v83
	v_lshlrev_b32_e32 v82, 16, v114
	v_and_b32_e32 v83, 0xffff0000, v114
	v_mul_f32_e32 v82, v82, v151
	v_mul_f32_e32 v83, v83, v151
	v_cvt_pk_bf16_f32 v114, v82, v83
	v_lshlrev_b32_e32 v82, 16, v115
	v_and_b32_e32 v83, 0xffff0000, v115
	v_mul_f32_e32 v82, v82, v151
	v_mul_f32_e32 v83, v83, v151
	v_cvt_pk_bf16_f32 v115, v82, v83
	ds_write2st64_b64 v10, v[108:109], v[110:111] offset1:1
	ds_write2st64_b64 v10, v[112:113], v[114:115] offset0:2 offset1:3
	v_add_u32_e32 v10, 0x800, v10
	v_lshlrev_b32_e32 v82, 16, v116
	v_and_b32_e32 v83, 0xffff0000, v116
	v_mul_f32_e32 v82, v82, v152
	v_mul_f32_e32 v83, v83, v152
	v_cvt_pk_bf16_f32 v116, v82, v83
	v_lshlrev_b32_e32 v82, 16, v117
	v_and_b32_e32 v83, 0xffff0000, v117
	v_mul_f32_e32 v82, v82, v152
	v_mul_f32_e32 v83, v83, v152
	v_cvt_pk_bf16_f32 v117, v82, v83
	v_lshlrev_b32_e32 v82, 16, v118
	v_and_b32_e32 v83, 0xffff0000, v118
	v_mul_f32_e32 v82, v82, v152
	v_mul_f32_e32 v83, v83, v152
	v_cvt_pk_bf16_f32 v118, v82, v83
	v_lshlrev_b32_e32 v82, 16, v119
	v_and_b32_e32 v83, 0xffff0000, v119
	v_mul_f32_e32 v82, v82, v152
	v_mul_f32_e32 v83, v83, v152
	v_cvt_pk_bf16_f32 v119, v82, v83
	v_lshlrev_b32_e32 v82, 16, v120
	v_and_b32_e32 v83, 0xffff0000, v120
	v_mul_f32_e32 v82, v82, v152
	v_mul_f32_e32 v83, v83, v152
	v_cvt_pk_bf16_f32 v120, v82, v83
	v_lshlrev_b32_e32 v82, 16, v121
	v_and_b32_e32 v83, 0xffff0000, v121
	v_mul_f32_e32 v82, v82, v152
	v_mul_f32_e32 v83, v83, v152
	v_cvt_pk_bf16_f32 v121, v82, v83
	v_lshlrev_b32_e32 v82, 16, v122
	v_and_b32_e32 v83, 0xffff0000, v122
	v_mul_f32_e32 v82, v82, v152
	v_mul_f32_e32 v83, v83, v152
	v_cvt_pk_bf16_f32 v122, v82, v83
	v_lshlrev_b32_e32 v82, 16, v123
	v_and_b32_e32 v83, 0xffff0000, v123
	v_mul_f32_e32 v82, v82, v152
	v_mul_f32_e32 v83, v83, v152
	v_cvt_pk_bf16_f32 v123, v82, v83
	ds_write2st64_b64 v10, v[116:117], v[118:119] offset1:1
	ds_write2st64_b64 v10, v[120:121], v[122:123] offset0:2 offset1:3
	v_add_u32_e32 v10, 0x800, v10
	v_lshlrev_b32_e32 v82, 16, v124
	v_and_b32_e32 v83, 0xffff0000, v124
	v_mul_f32_e32 v82, v82, v153
	v_mul_f32_e32 v83, v83, v153
	v_cvt_pk_bf16_f32 v124, v82, v83
	v_lshlrev_b32_e32 v82, 16, v125
	v_and_b32_e32 v83, 0xffff0000, v125
	v_mul_f32_e32 v82, v82, v153
	v_mul_f32_e32 v83, v83, v153
	v_cvt_pk_bf16_f32 v125, v82, v83
	v_lshlrev_b32_e32 v82, 16, v126
	v_and_b32_e32 v83, 0xffff0000, v126
	v_mul_f32_e32 v82, v82, v153
	v_mul_f32_e32 v83, v83, v153
	v_cvt_pk_bf16_f32 v126, v82, v83
	v_lshlrev_b32_e32 v82, 16, v127
	v_and_b32_e32 v83, 0xffff0000, v127
	v_mul_f32_e32 v82, v82, v153
	v_mul_f32_e32 v83, v83, v153
	v_cvt_pk_bf16_f32 v127, v82, v83
	v_lshlrev_b32_e32 v82, 16, v128
	v_and_b32_e32 v83, 0xffff0000, v128
	v_mul_f32_e32 v82, v82, v153
	v_mul_f32_e32 v83, v83, v153
	v_cvt_pk_bf16_f32 v128, v82, v83
	v_lshlrev_b32_e32 v82, 16, v129
	v_and_b32_e32 v83, 0xffff0000, v129
	v_mul_f32_e32 v82, v82, v153
	v_mul_f32_e32 v83, v83, v153
	v_cvt_pk_bf16_f32 v129, v82, v83
	v_lshlrev_b32_e32 v82, 16, v130
	v_and_b32_e32 v83, 0xffff0000, v130
	v_mul_f32_e32 v82, v82, v153
	v_mul_f32_e32 v83, v83, v153
	v_cvt_pk_bf16_f32 v130, v82, v83
	v_lshlrev_b32_e32 v82, 16, v131
	v_and_b32_e32 v83, 0xffff0000, v131
	v_mul_f32_e32 v82, v82, v153
	v_mul_f32_e32 v83, v83, v153
	v_cvt_pk_bf16_f32 v131, v82, v83
	ds_write2st64_b64 v10, v[124:125], v[126:127] offset1:1
	ds_write2st64_b64 v10, v[128:129], v[130:131] offset0:2 offset1:3
	v_add_u32_e32 v10, 0x800, v10
	v_lshlrev_b32_e32 v82, 16, v132
	v_and_b32_e32 v83, 0xffff0000, v132
	v_mul_f32_e32 v82, v82, v154
	v_mul_f32_e32 v83, v83, v154
	v_cvt_pk_bf16_f32 v132, v82, v83
	v_lshlrev_b32_e32 v82, 16, v133
	v_and_b32_e32 v83, 0xffff0000, v133
	v_mul_f32_e32 v82, v82, v154
	v_mul_f32_e32 v83, v83, v154
	v_cvt_pk_bf16_f32 v133, v82, v83
	v_lshlrev_b32_e32 v82, 16, v134
	v_and_b32_e32 v83, 0xffff0000, v134
	v_mul_f32_e32 v82, v82, v154
	v_mul_f32_e32 v83, v83, v154
	v_cvt_pk_bf16_f32 v134, v82, v83
	v_lshlrev_b32_e32 v82, 16, v135
	v_and_b32_e32 v83, 0xffff0000, v135
	v_mul_f32_e32 v82, v82, v154
	v_mul_f32_e32 v83, v83, v154
	v_cvt_pk_bf16_f32 v135, v82, v83
	v_lshlrev_b32_e32 v82, 16, v136
	v_and_b32_e32 v83, 0xffff0000, v136
	v_mul_f32_e32 v82, v82, v154
	v_mul_f32_e32 v83, v83, v154
	v_cvt_pk_bf16_f32 v136, v82, v83
	v_lshlrev_b32_e32 v82, 16, v137
	v_and_b32_e32 v83, 0xffff0000, v137
	v_mul_f32_e32 v82, v82, v154
	v_mul_f32_e32 v83, v83, v154
	v_cvt_pk_bf16_f32 v137, v82, v83
	v_lshlrev_b32_e32 v82, 16, v138
	v_and_b32_e32 v83, 0xffff0000, v138
	v_mul_f32_e32 v82, v82, v154
	v_mul_f32_e32 v83, v83, v154
	v_cvt_pk_bf16_f32 v138, v82, v83
	v_lshlrev_b32_e32 v82, 16, v139
	v_and_b32_e32 v83, 0xffff0000, v139
	v_mul_f32_e32 v82, v82, v154
	v_mul_f32_e32 v83, v83, v154
	v_cvt_pk_bf16_f32 v139, v82, v83
	ds_write2st64_b64 v10, v[132:133], v[134:135] offset1:1
	ds_write2st64_b64 v10, v[136:137], v[138:139] offset0:2 offset1:3
	v_add_u32_e32 v10, 0x800, v10
	v_lshlrev_b32_e32 v82, 16, v140
	v_and_b32_e32 v83, 0xffff0000, v140
	v_mul_f32_e32 v82, v82, v155
	v_mul_f32_e32 v83, v83, v155
	v_cvt_pk_bf16_f32 v140, v82, v83
	v_lshlrev_b32_e32 v82, 16, v141
	v_and_b32_e32 v83, 0xffff0000, v141
	v_mul_f32_e32 v82, v82, v155
	v_mul_f32_e32 v83, v83, v155
	v_cvt_pk_bf16_f32 v141, v82, v83
	v_lshlrev_b32_e32 v82, 16, v142
	v_and_b32_e32 v83, 0xffff0000, v142
	v_mul_f32_e32 v82, v82, v155
	v_mul_f32_e32 v83, v83, v155
	v_cvt_pk_bf16_f32 v142, v82, v83
	v_lshlrev_b32_e32 v82, 16, v143
	v_and_b32_e32 v83, 0xffff0000, v143
	v_mul_f32_e32 v82, v82, v155
	v_mul_f32_e32 v83, v83, v155
	v_cvt_pk_bf16_f32 v143, v82, v83
	v_lshlrev_b32_e32 v82, 16, v144
	v_and_b32_e32 v83, 0xffff0000, v144
	v_mul_f32_e32 v82, v82, v155
	v_mul_f32_e32 v83, v83, v155
	v_cvt_pk_bf16_f32 v144, v82, v83
	v_lshlrev_b32_e32 v82, 16, v145
	v_and_b32_e32 v83, 0xffff0000, v145
	v_mul_f32_e32 v82, v82, v155
	v_mul_f32_e32 v83, v83, v155
	v_cvt_pk_bf16_f32 v145, v82, v83
	v_lshlrev_b32_e32 v82, 16, v146
	v_and_b32_e32 v83, 0xffff0000, v146
	v_mul_f32_e32 v82, v82, v155
	v_mul_f32_e32 v83, v83, v155
	v_cvt_pk_bf16_f32 v146, v82, v83
	v_lshlrev_b32_e32 v82, 16, v147
	v_and_b32_e32 v83, 0xffff0000, v147
	v_mul_f32_e32 v82, v82, v155
	v_mul_f32_e32 v83, v83, v155
	v_cvt_pk_bf16_f32 v147, v82, v83
	ds_write2st64_b64 v10, v[140:141], v[142:143] offset1:1
	ds_write2st64_b64 v10, v[144:145], v[146:147] offset0:2 offset1:3
	v_add_u32_e32 v10, 0x800, v10
	s_waitcnt lgkmcnt(0)
	s_barrier
	ds_read2st64_b32 v[56:57], v17 offset1:8
	ds_read2st64_b32 v[58:59], v17 offset0:16 offset1:24
	ds_read2st64_b32 v[60:61], v17 offset0:32 offset1:40
	ds_read2st64_b32 v[62:63], v17 offset0:48 offset1:56
	s_lshl_b32 s8, s0, 6
	s_ashr_i32 s9, s8, 31
	s_lshl_b64 s[8:9], s[8:9], 1
	s_waitcnt lgkmcnt(3)
	v_and_b32_e32 v51, 0xffff, v56
	v_lshl_or_b32 v52, v57, 16, v51
	s_waitcnt lgkmcnt(2)
	v_and_b32_e32 v51, 0xffff, v58
	v_lshl_or_b32 v53, v59, 16, v51
	s_waitcnt lgkmcnt(1)
	v_and_b32_e32 v51, 0xffff, v60
	v_lshl_or_b32 v54, v61, 16, v51
	s_waitcnt lgkmcnt(0)
	v_and_b32_e32 v51, 0xffff, v62
	v_lshl_or_b32 v55, v63, 16, v51
	v_lshrrev_b32_e32 v51, 16, v56
	v_and_or_b32 v56, v57, s91, v51
	v_lshrrev_b32_e32 v51, 16, v58
	v_and_or_b32 v57, v59, s91, v51
	v_lshrrev_b32_e32 v51, 16, v60
	v_and_or_b32 v58, v61, s91, v51
	v_lshrrev_b32_e32 v51, 16, v62
	ds_read2st64_b32 v[60:61], v17 offset0:64 offset1:72
	v_lshl_add_u64 v[8:9], v[2:3], 0, s[8:9]
	v_lshl_add_u64 v[10:11], v[4:5], 0, s[8:9]
	v_and_or_b32 v59, v63, s91, v51
	global_store_dwordx4 v[8:9], v[52:55], off
	global_store_dwordx4 v[10:11], v[56:59], off
	ds_read2st64_b32 v[58:59], v17 offset0:80 offset1:88
	ds_read2st64_b32 v[62:63], v17 offset0:96 offset1:104
	ds_read2st64_b32 v[64:65], v17 offset0:112 offset1:120
	s_waitcnt lgkmcnt(3)
	v_and_b32_e32 v51, 0xffff, v60
	v_lshl_or_b32 v52, v61, 16, v51
	s_waitcnt lgkmcnt(2)
	v_and_b32_e32 v51, 0xffff, v58
	v_lshl_or_b32 v53, v59, 16, v51
	s_waitcnt lgkmcnt(1)
	v_and_b32_e32 v51, 0xffff, v62
	v_lshl_or_b32 v54, v63, 16, v51
	s_waitcnt lgkmcnt(0)
	v_and_b32_e32 v51, 0xffff, v64
	v_lshl_or_b32 v55, v65, 16, v51
	v_lshrrev_b32_e32 v51, 16, v60
	v_and_or_b32 v56, v61, s91, v51
	v_lshrrev_b32_e32 v51, 16, v58
	v_and_or_b32 v57, v59, s91, v51
	v_lshrrev_b32_e32 v51, 16, v62
	v_and_or_b32 v58, v63, s91, v51
	v_lshrrev_b32_e32 v51, 16, v64
	ds_read2st64_b32 v[60:61], v17 offset0:128 offset1:136
	v_and_or_b32 v59, v65, s91, v51
	global_store_dwordx4 v[8:9], v[52:55], off offset:16
	global_store_dwordx4 v[10:11], v[56:59], off offset:16
	ds_read2st64_b32 v[58:59], v17 offset0:144 offset1:152
	ds_read2st64_b32 v[62:63], v17 offset0:160 offset1:168
	ds_read2st64_b32 v[64:65], v17 offset0:176 offset1:184
	s_waitcnt lgkmcnt(3)
	v_and_b32_e32 v51, 0xffff, v60
	v_lshl_or_b32 v52, v61, 16, v51
	s_waitcnt lgkmcnt(2)
	v_and_b32_e32 v51, 0xffff, v58
	v_lshl_or_b32 v53, v59, 16, v51
	s_waitcnt lgkmcnt(1)
	v_and_b32_e32 v51, 0xffff, v62
	v_lshl_or_b32 v54, v63, 16, v51
	s_waitcnt lgkmcnt(0)
	v_and_b32_e32 v51, 0xffff, v64
	v_lshl_or_b32 v55, v65, 16, v51
	v_lshrrev_b32_e32 v51, 16, v60
	v_and_or_b32 v56, v61, s91, v51
	v_lshrrev_b32_e32 v51, 16, v58
	v_and_or_b32 v57, v59, s91, v51
	v_lshrrev_b32_e32 v51, 16, v62
	v_and_or_b32 v58, v63, s91, v51
	v_lshrrev_b32_e32 v51, 16, v64
	ds_read2st64_b32 v[60:61], v17 offset0:192 offset1:200
	v_and_or_b32 v59, v65, s91, v51
	global_store_dwordx4 v[8:9], v[52:55], off offset:32
	global_store_dwordx4 v[10:11], v[56:59], off offset:32
	ds_read2st64_b32 v[58:59], v17 offset0:208 offset1:216
	ds_read2st64_b32 v[62:63], v17 offset0:224 offset1:232
	ds_read2st64_b32 v[64:65], v17 offset0:240 offset1:248
	s_waitcnt lgkmcnt(3)
	v_and_b32_e32 v51, 0xffff, v60
	v_lshl_or_b32 v52, v61, 16, v51
	s_waitcnt lgkmcnt(2)
	v_and_b32_e32 v51, 0xffff, v58
	v_lshl_or_b32 v53, v59, 16, v51
	s_waitcnt lgkmcnt(1)
	v_and_b32_e32 v51, 0xffff, v62
	v_lshl_or_b32 v54, v63, 16, v51
	s_waitcnt lgkmcnt(0)
	v_and_b32_e32 v51, 0xffff, v64
	v_lshl_or_b32 v55, v65, 16, v51
	v_lshrrev_b32_e32 v51, 16, v60
	v_and_or_b32 v56, v61, s91, v51
	v_lshrrev_b32_e32 v51, 16, v58
	v_and_or_b32 v57, v59, s91, v51
	v_lshrrev_b32_e32 v51, 16, v62
	v_and_or_b32 v58, v63, s91, v51
	v_lshrrev_b32_e32 v51, 16, v64
	v_and_or_b32 v59, v65, s91, v51
	global_store_dwordx4 v[8:9], v[52:55], off offset:48
	global_store_dwordx4 v[10:11], v[56:59], off offset:48
	ds_read_b32 v51, v18
	ds_read_b32 v56, v19
	ds_read_b32 v57, v20
	ds_read_b32 v58, v21
	ds_read_b32 v59, v22
	ds_read_b32 v60, v23
	ds_read_b32 v61, v24
	ds_read_b32 v62, v25
	s_waitcnt lgkmcnt(7)
	v_and_b32_e32 v52, 0xffff, v51
	v_lshrrev_b32_e32 v51, 16, v51
	s_waitcnt lgkmcnt(6)
	v_lshl_or_b32 v52, v56, 16, v52
	v_and_or_b32 v56, v56, s91, v51
	s_waitcnt lgkmcnt(5)
	v_lshrrev_b32_e32 v51, 16, v57
	v_and_b32_e32 v53, 0xffff, v57
	s_waitcnt lgkmcnt(3)
	v_and_b32_e32 v54, 0xffff, v59
	s_waitcnt lgkmcnt(1)
	v_and_b32_e32 v55, 0xffff, v61
	v_and_or_b32 v57, v58, s91, v51
	v_lshrrev_b32_e32 v51, 16, v59
	v_lshl_or_b32 v53, v58, 16, v53
	v_lshl_or_b32 v54, v60, 16, v54
	s_waitcnt lgkmcnt(0)
	v_lshl_or_b32 v55, v62, 16, v55
	v_and_or_b32 v58, v60, s91, v51
	v_lshrrev_b32_e32 v51, 16, v61
	v_and_or_b32 v59, v62, s91, v51
	global_store_dwordx4 v[8:9], v[52:55], off offset:64
	global_store_dwordx4 v[10:11], v[56:59], off offset:64
	ds_read_b32 v51, v26
	ds_read_b32 v56, v27
	ds_read_b32 v57, v28
	ds_read_b32 v58, v29
	ds_read_b32 v59, v30
	ds_read_b32 v60, v31
	ds_read_b32 v61, v32
	ds_read_b32 v62, v33
	s_waitcnt lgkmcnt(7)
	v_and_b32_e32 v52, 0xffff, v51
	v_lshrrev_b32_e32 v51, 16, v51
	s_waitcnt lgkmcnt(6)
	v_lshl_or_b32 v52, v56, 16, v52
	v_and_or_b32 v56, v56, s91, v51
	s_waitcnt lgkmcnt(5)
	v_lshrrev_b32_e32 v51, 16, v57
	v_and_b32_e32 v53, 0xffff, v57
	s_waitcnt lgkmcnt(3)
	v_and_b32_e32 v54, 0xffff, v59
	s_waitcnt lgkmcnt(1)
	v_and_b32_e32 v55, 0xffff, v61
	v_and_or_b32 v57, v58, s91, v51
	v_lshrrev_b32_e32 v51, 16, v59
	v_lshl_or_b32 v53, v58, 16, v53
	v_lshl_or_b32 v54, v60, 16, v54
	s_waitcnt lgkmcnt(0)
	v_lshl_or_b32 v55, v62, 16, v55
	v_and_or_b32 v58, v60, s91, v51
	v_lshrrev_b32_e32 v51, 16, v61
	v_and_or_b32 v59, v62, s91, v51
	global_store_dwordx4 v[8:9], v[52:55], off offset:80
	global_store_dwordx4 v[10:11], v[56:59], off offset:80
	ds_read_b32 v51, v34
	ds_read_b32 v56, v35
	ds_read_b32 v57, v36
	ds_read_b32 v58, v37
	ds_read_b32 v59, v38
	ds_read_b32 v60, v39
	ds_read_b32 v61, v40
	ds_read_b32 v62, v41
	s_waitcnt lgkmcnt(7)
	v_and_b32_e32 v52, 0xffff, v51
	v_lshrrev_b32_e32 v51, 16, v51
	s_waitcnt lgkmcnt(6)
	v_lshl_or_b32 v52, v56, 16, v52
	v_and_or_b32 v56, v56, s91, v51
	s_waitcnt lgkmcnt(5)
	v_lshrrev_b32_e32 v51, 16, v57
	v_and_b32_e32 v53, 0xffff, v57
	s_waitcnt lgkmcnt(3)
	v_and_b32_e32 v54, 0xffff, v59
	s_waitcnt lgkmcnt(1)
	v_and_b32_e32 v55, 0xffff, v61
	v_and_or_b32 v57, v58, s91, v51
	v_lshrrev_b32_e32 v51, 16, v59
	v_lshl_or_b32 v53, v58, 16, v53
	v_lshl_or_b32 v54, v60, 16, v54
	s_waitcnt lgkmcnt(0)
	v_lshl_or_b32 v55, v62, 16, v55
	v_and_or_b32 v58, v60, s91, v51
	v_lshrrev_b32_e32 v51, 16, v61
	v_and_or_b32 v59, v62, s91, v51
	global_store_dwordx4 v[8:9], v[52:55], off offset:96
	global_store_dwordx4 v[10:11], v[56:59], off offset:96
	ds_read_b32 v51, v42
	ds_read_b32 v56, v43
	ds_read_b32 v57, v44
	ds_read_b32 v58, v45
	ds_read_b32 v59, v46
	ds_read_b32 v60, v47
	ds_read_b32 v61, v48
	ds_read_b32 v62, v49
	s_waitcnt lgkmcnt(7)
	v_and_b32_e32 v52, 0xffff, v51
	v_lshrrev_b32_e32 v51, 16, v51
	s_waitcnt lgkmcnt(6)
	v_lshl_or_b32 v52, v56, 16, v52
	v_and_or_b32 v56, v56, s91, v51
	s_waitcnt lgkmcnt(5)
	v_lshrrev_b32_e32 v51, 16, v57
	v_and_b32_e32 v53, 0xffff, v57
	s_waitcnt lgkmcnt(3)
	v_and_b32_e32 v54, 0xffff, v59
	s_waitcnt lgkmcnt(1)
	v_and_b32_e32 v55, 0xffff, v61
	v_and_or_b32 v57, v58, s91, v51
	v_lshrrev_b32_e32 v51, 16, v59
	s_add_i32 s0, s0, s78
	s_add_i32 s6, s6, s35
	v_lshl_or_b32 v53, v58, 16, v53
	v_lshl_or_b32 v54, v60, 16, v54
	s_waitcnt lgkmcnt(0)
	v_lshl_or_b32 v55, v62, 16, v55
	v_and_or_b32 v58, v60, s91, v51
	v_lshrrev_b32_e32 v51, 16, v61
	s_cmpk_gt_i32 s0, 0xbf
	v_and_or_b32 v59, v62, s91, v51
	global_store_dwordx4 v[8:9], v[52:55], off offset:112
	global_store_dwordx4 v[10:11], v[56:59], off offset:112
	s_barrier
	s_cbranch_scc0 .LBB0_119

.LBB0_285:
	v_sub_f32_e32 v51, s61, v54
	s_waitcnt vmcnt(8)
	v_add_f32_e32 v50, v50, v51
	v_sub_f32_e32 v51, s61, v55
	v_add_f32_e32 v0, v0, v51
	v_max_f32_e32 v51, v50, v0
	ds_bpermute_b32 v52, v141, v51
	v_add_f32_e32 v53, s61, v151
	s_ashr_i32 s61, s60, 31
	s_lshl_b64 s[52:53], s[60:61], 1
	s_add_u32 s60, s93, s52
	s_waitcnt lgkmcnt(0)
	v_max_f32_e32 v52, v52, v52
	v_max_f32_e32 v51, v51, v52
	ds_bpermute_b32 v52, v142, v51
	s_addc_u32 s61, s94, s53
	s_waitcnt lgkmcnt(0)
	v_max_f32_e32 v52, v52, v52
	v_max_f32_e32 v51, v51, v52
	ds_bpermute_b32 v52, v143, v51
	s_waitcnt lgkmcnt(0)
	v_max_f32_e32 v52, v52, v52
	v_max_f32_e32 v51, v51, v52
	ds_bpermute_b32 v52, v144, v51
	s_waitcnt lgkmcnt(0)
	v_max_f32_e32 v52, v52, v52
	v_max_f32_e32 v51, v51, v52
	ds_bpermute_b32 v52, v145, v51
	s_waitcnt lgkmcnt(0)
	v_max_f32_e32 v52, v52, v52
	v_max_f32_e32 v51, v51, v52
	ds_bpermute_b32 v52, v146, v51
	s_waitcnt lgkmcnt(0)
	v_max3_f32 v153, v53, v51, v52
	v_sub_f32_e32 v50, v50, v153
	v_sub_f32_e32 v0, v0, v153
	v_mul_f32_e32 v50, 0x3fb8aa3b, v50
	v_mul_f32_e32 v0, 0x3fb8aa3b, v0
	v_exp_f32_e32 v50, v50
	v_exp_f32_e32 v51, v0
	v_sub_f32_e32 v0, v53, v153
	v_mul_f32_e32 v0, 0x3fb8aa3b, v0
	v_exp_f32_e32 v0, v0
	ds_write_b64 v147, v[50:51]
	ds_read_b128 v[82:85], v148
	ds_read_b128 v[86:89], v148 offset:16
	s_waitcnt vmcnt(7)
	v_mov_b32_e32 v90, v180
	v_mov_b32_e32 v91, v181
	v_mov_b32_e32 v92, v182
	v_mov_b32_e32 v93, v183
	v_pk_mul_f32 v[80:81], v[48:49], v[0:1] op_sel_hi:[1,0]
	v_pk_mul_f32 v[78:79], v[46:47], v[0:1] op_sel_hi:[1,0]
	v_pk_mul_f32 v[76:77], v[44:45], v[0:1] op_sel_hi:[1,0]
	v_pk_mul_f32 v[74:75], v[42:43], v[0:1] op_sel_hi:[1,0]
	v_pk_mul_f32 v[72:73], v[32:33], v[0:1] op_sel_hi:[1,0]
	v_pk_mul_f32 v[70:71], v[30:31], v[0:1] op_sel_hi:[1,0]
	v_pk_mul_f32 v[68:69], v[28:29], v[0:1] op_sel_hi:[1,0]
	v_pk_mul_f32 v[66:67], v[26:27], v[0:1] op_sel_hi:[1,0]
	v_pk_mul_f32 v[64:65], v[16:17], v[0:1] op_sel_hi:[1,0]
	v_pk_mul_f32 v[62:63], v[14:15], v[0:1] op_sel_hi:[1,0]
	v_pk_mul_f32 v[60:61], v[12:13], v[0:1] op_sel_hi:[1,0]
	v_pk_mul_f32 v[58:59], v[10:11], v[0:1] op_sel_hi:[1,0]
	v_pk_mul_f32 v[56:57], v[8:9], v[0:1] op_sel_hi:[1,0]
	v_pk_mul_f32 v[54:55], v[6:7], v[0:1] op_sel_hi:[1,0]
	v_pk_mul_f32 v[52:53], v[4:5], v[0:1] op_sel_hi:[1,0]
	v_pk_mul_f32 v[50:51], v[2:3], v[0:1] op_sel_hi:[1,0]
	s_waitcnt vmcnt(4)
	v_lshlrev_b32_e32 v94, 16, v90
	v_and_b32_e32 v95, 0xffff0000, v90
	v_lshlrev_b32_e32 v90, 16, v91
	v_and_b32_e32 v91, 0xffff0000, v91
	s_waitcnt lgkmcnt(1)
	v_pk_mul_f32 v[84:85], v[84:85], v[90:91]
	v_lshlrev_b32_e32 v90, 16, v92
	v_and_b32_e32 v91, 0xffff0000, v92
	v_pk_mul_f32 v[82:83], v[82:83], v[94:95]
	s_waitcnt lgkmcnt(0)
	v_pk_mul_f32 v[86:87], v[86:87], v[90:91]
	v_lshlrev_b32_e32 v90, 16, v93
	v_and_b32_e32 v91, 0xffff0000, v93
	v_pk_mul_f32 v[88:89], v[88:89], v[90:91]
	v_mov_b32_e32 v90, v82
	v_mov_b32_e32 v91, v86
	v_mov_b32_e32 v92, v83
	v_mov_b32_e32 v93, v87
	v_pk_add_f32 v[90:91], v[90:91], v[92:93]
	v_mov_b32_e32 v92, v84
	v_mov_b32_e32 v93, v88
	v_mov_b32_e32 v94, v85
	v_mov_b32_e32 v95, v89
	v_pk_add_f32 v[92:93], v[92:93], v[94:95]
	v_cvt_pk_bf16_f32 v82, v82, v83
	v_pk_add_f32 v[90:91], v[90:91], v[92:93]
	v_cvt_pk_bf16_f32 v83, v84, v85
	v_pk_add_f32 v[108:109], v[90:91], v[90:91] op_sel:[0,1] op_sel_hi:[1,0]
	v_cvt_pk_bf16_f32 v84, v86, v87
	v_cvt_pk_bf16_f32 v85, v88, v89
	ds_read_b128 v[86:89], v148 offset:128
	ds_read_b128 v[90:93], v148 offset:144
	s_waitcnt vmcnt(6)
	v_mov_b32_e32 v94, v184
	v_mov_b32_e32 v95, v185
	v_mov_b32_e32 v96, v186
	v_mov_b32_e32 v97, v187
	s_waitcnt vmcnt(4)
	v_lshlrev_b32_e32 v98, 16, v94
	v_and_b32_e32 v99, 0xffff0000, v94
	v_lshlrev_b32_e32 v94, 16, v95
	v_and_b32_e32 v95, 0xffff0000, v95
	s_waitcnt lgkmcnt(1)
	v_pk_mul_f32 v[88:89], v[88:89], v[94:95]
	v_lshlrev_b32_e32 v94, 16, v96
	v_and_b32_e32 v95, 0xffff0000, v96
	v_pk_mul_f32 v[86:87], v[86:87], v[98:99]
	s_waitcnt lgkmcnt(0)
	v_pk_mul_f32 v[90:91], v[90:91], v[94:95]
	v_lshlrev_b32_e32 v94, 16, v97
	v_and_b32_e32 v95, 0xffff0000, v97
	v_pk_mul_f32 v[92:93], v[92:93], v[94:95]
	v_mov_b32_e32 v94, v86
	v_mov_b32_e32 v95, v88
	v_mov_b32_e32 v96, v87
	v_mov_b32_e32 v97, v89
	v_pk_add_f32 v[94:95], v[94:95], v[96:97]
	v_mov_b32_e32 v96, v91
	v_pk_add_f32 v[110:111], v[94:95], v[94:95] op_sel:[0,1] op_sel_hi:[1,0]
	v_mov_b32_e32 v94, v90
	v_mov_b32_e32 v95, v92
	v_mov_b32_e32 v97, v93
	v_pk_add_f32 v[94:95], v[94:95], v[96:97]
	v_cvt_pk_bf16_f32 v86, v86, v87
	v_pk_add_f32 v[112:113], v[94:95], v[94:95] op_sel:[0,1] op_sel_hi:[1,0]
	v_cvt_pk_bf16_f32 v87, v88, v89
	v_cvt_pk_bf16_f32 v88, v90, v91
	v_cvt_pk_bf16_f32 v89, v92, v93
	ds_read_b128 v[94:97], v148 offset:256
	ds_read_b128 v[90:93], v148 offset:272
	s_waitcnt vmcnt(5)
	v_mov_b32_e32 v98, v188
	v_mov_b32_e32 v99, v189
	v_mov_b32_e32 v100, v190
	v_mov_b32_e32 v101, v191
	s_waitcnt vmcnt(4)
	v_lshlrev_b32_e32 v104, 16, v98
	v_and_b32_e32 v105, 0xffff0000, v98
	v_lshlrev_b32_e32 v98, 16, v99
	v_and_b32_e32 v99, 0xffff0000, v99
	v_lshlrev_b32_e32 v114, 16, v100
	v_and_b32_e32 v115, 0xffff0000, v100
	v_lshlrev_b32_e32 v100, 16, v101
	v_and_b32_e32 v101, 0xffff0000, v101
	s_waitcnt lgkmcnt(1)
	v_pk_mul_f32 v[122:123], v[94:95], v[104:105]
	v_pk_mul_f32 v[154:155], v[96:97], v[98:99]
	s_waitcnt lgkmcnt(0)
	v_pk_mul_f32 v[158:159], v[92:93], v[100:101]
	v_pk_fma_f32 v[118:119], v[94:95], v[104:105], v[122:123] op_sel:[0,0,1] op_sel_hi:[1,1,0]
	v_pk_fma_f32 v[120:121], v[96:97], v[98:99], v[154:155] op_sel:[0,0,1] op_sel_hi:[1,1,0]
	v_pk_fma_f32 v[116:117], v[92:93], v[100:101], v[158:159] op_sel:[0,0,1] op_sel_hi:[1,1,0]
	ds_read_b128 v[98:101], v148 offset:384
	ds_read_b128 v[94:97], v148 offset:400
	s_waitcnt vmcnt(4)
	v_mov_b32_e32 v102, v192
	v_mov_b32_e32 v103, v193
	v_mov_b32_e32 v104, v194
	v_mov_b32_e32 v105, v195
	v_pk_mul_f32 v[156:157], v[90:91], v[114:115]
	v_cvt_pk_bf16_f32 v93, v158, v159
	v_pk_fma_f32 v[114:115], v[90:91], v[114:115], v[156:157] op_sel:[0,0,1] op_sel_hi:[1,1,0]
	v_cvt_pk_bf16_f32 v90, v122, v123
	v_cvt_pk_bf16_f32 v91, v154, v155
	v_cvt_pk_bf16_f32 v92, v156, v157
	s_waitcnt vmcnt(4)
	v_lshlrev_b32_e32 v122, 16, v102
	v_and_b32_e32 v123, 0xffff0000, v102
	v_lshlrev_b32_e32 v102, 16, v103
	v_and_b32_e32 v103, 0xffff0000, v103
	s_waitcnt lgkmcnt(1)
	v_pk_mul_f32 v[98:99], v[98:99], v[122:123]
	v_pk_mul_f32 v[122:123], v[100:101], v[102:103]
	v_lshlrev_b32_e32 v100, 16, v104
	v_and_b32_e32 v101, 0xffff0000, v104
	s_waitcnt lgkmcnt(0)
	v_pk_mul_f32 v[102:103], v[94:95], v[100:101]
	v_lshlrev_b32_e32 v94, 16, v105
	v_and_b32_e32 v95, 0xffff0000, v105
	v_pk_mul_f32 v[100:101], v[96:97], v[94:95]
	v_cvt_pk_bf16_f32 v94, v98, v99
	v_cvt_pk_bf16_f32 v95, v122, v123
	v_cvt_pk_bf16_f32 v96, v102, v103
	v_cvt_pk_bf16_f32 v97, v100, v101
	ds_read_b128 v[154:157], v149
	s_waitcnt lgkmcnt(0)
	v_mfma_f32_16x16x32_bf16 v[78:81], v[154:157], v[82:85], v[78:81]
	ds_read_b128 v[154:157], v149 offset:4352
	s_waitcnt lgkmcnt(0)
	v_mfma_f32_16x16x32_bf16 v[154:157], v[154:157], v[82:85], v[74:77]
	s_nop 2
	ds_read_b128 v[74:77], v149 offset:64
	s_waitcnt lgkmcnt(0)
	v_mfma_f32_16x16x32_bf16 v[74:77], v[74:77], v[86:89], v[78:81]
	s_nop 2
	ds_read_b128 v[78:81], v149 offset:128
	s_waitcnt lgkmcnt(0)
	v_mfma_f32_16x16x32_bf16 v[74:77], v[78:81], v[90:93], v[74:77]
	ds_read_b128 v[78:81], v149 offset:192
	s_waitcnt lgkmcnt(0)
	v_mfma_f32_16x16x32_bf16 v[74:77], v[78:81], v[94:97], v[74:77]
	ds_read_b128 v[78:81], v149 offset:4416
	s_waitcnt lgkmcnt(0)
	v_mfma_f32_16x16x32_bf16 v[78:81], v[78:81], v[86:89], v[154:157]
	s_nop 2
	ds_read_b128 v[154:157], v149 offset:4480
	s_waitcnt lgkmcnt(0)
	v_mfma_f32_16x16x32_bf16 v[78:81], v[154:157], v[90:93], v[78:81]
	ds_read_b128 v[154:157], v149 offset:4544
	s_waitcnt lgkmcnt(0)
	v_mfma_f32_16x16x32_bf16 v[78:81], v[154:157], v[94:97], v[78:81]
	ds_read_b128 v[154:157], v149 offset:8704
	s_waitcnt lgkmcnt(0)
	v_mfma_f32_16x16x32_bf16 v[70:73], v[154:157], v[82:85], v[70:73]
	ds_read_b128 v[154:157], v149 offset:8768
	s_waitcnt lgkmcnt(0)
	v_mfma_f32_16x16x32_bf16 v[70:73], v[154:157], v[86:89], v[70:73]
	ds_read_b128 v[154:157], v149 offset:8832
	s_waitcnt lgkmcnt(0)
	v_mfma_f32_16x16x32_bf16 v[70:73], v[154:157], v[90:93], v[70:73]
	ds_read_b128 v[154:157], v149 offset:8896
	s_waitcnt lgkmcnt(0)
	v_mfma_f32_16x16x32_bf16 v[70:73], v[154:157], v[94:97], v[70:73]
	ds_read_b128 v[154:157], v149 offset:13056
	s_waitcnt lgkmcnt(0)
	v_mfma_f32_16x16x32_bf16 v[66:69], v[154:157], v[82:85], v[66:69]
	ds_read_b128 v[154:157], v149 offset:13120
	s_waitcnt lgkmcnt(0)
	v_mfma_f32_16x16x32_bf16 v[66:69], v[154:157], v[86:89], v[66:69]
	ds_read_b128 v[154:157], v149 offset:13184
	s_waitcnt lgkmcnt(0)
	v_mfma_f32_16x16x32_bf16 v[66:69], v[154:157], v[90:93], v[66:69]
	ds_read_b128 v[154:157], v149 offset:13248
	s_waitcnt lgkmcnt(0)
	v_mfma_f32_16x16x32_bf16 v[66:69], v[154:157], v[94:97], v[66:69]
	ds_read_b128 v[154:157], v149 offset:17408
	v_mov_b32_e32 v119, v102
	v_mov_b32_e32 v121, v103
	v_mov_b32_e32 v115, v100
	v_mov_b32_e32 v117, v101
	v_mov_b32_e32 v111, v122
	v_mov_b32_e32 v113, v123
	v_mov_b32_e32 v109, v98
	v_mov_b32_e32 v98, v1
	s_waitcnt lgkmcnt(0)
	v_mfma_f32_16x16x32_bf16 v[62:65], v[154:157], v[82:85], v[62:65]
	ds_read_b128 v[154:157], v149 offset:17472
	s_waitcnt lgkmcnt(0)
	v_mfma_f32_16x16x32_bf16 v[62:65], v[154:157], v[86:89], v[62:65]
	ds_read_b128 v[154:157], v149 offset:17536
	s_waitcnt lgkmcnt(0)
	v_mfma_f32_16x16x32_bf16 v[62:65], v[154:157], v[90:93], v[62:65]
	ds_read_b128 v[154:157], v149 offset:17600
	s_waitcnt lgkmcnt(0)
	v_mfma_f32_16x16x32_bf16 v[62:65], v[154:157], v[94:97], v[62:65]
	ds_read_b128 v[154:157], v149 offset:21952
	ds_read_b128 v[158:161], v149 offset:21888
	ds_read_b128 v[162:165], v149 offset:21824
	ds_read_b128 v[170:173], v149 offset:21760
	s_waitcnt lgkmcnt(0)
	v_mfma_f32_16x16x32_bf16 v[58:61], v[170:173], v[82:85], v[58:61]
	v_mfma_f32_16x16x32_bf16 v[58:61], v[162:165], v[86:89], v[58:61]
	v_mfma_f32_16x16x32_bf16 v[58:61], v[158:161], v[90:93], v[58:61]
	v_mfma_f32_16x16x32_bf16 v[58:61], v[154:157], v[94:97], v[58:61]
	ds_read_b128 v[154:157], v149 offset:26304
	ds_read_b128 v[158:161], v149 offset:26240
	ds_read_b128 v[162:165], v149 offset:26176
	ds_read_b128 v[170:173], v149 offset:26112
	s_waitcnt lgkmcnt(0)
	v_mfma_f32_16x16x32_bf16 v[54:57], v[170:173], v[82:85], v[54:57]
	v_mfma_f32_16x16x32_bf16 v[54:57], v[162:165], v[86:89], v[54:57]
	v_mfma_f32_16x16x32_bf16 v[54:57], v[158:161], v[90:93], v[54:57]
	v_mfma_f32_16x16x32_bf16 v[54:57], v[154:157], v[94:97], v[54:57]
	ds_read_b128 v[154:157], v149 offset:30656
	ds_read_b128 v[158:161], v149 offset:30592
	ds_read_b128 v[162:165], v149 offset:30528
	ds_read_b128 v[170:173], v149 offset:30464
	s_waitcnt lgkmcnt(0)
	v_mfma_f32_16x16x32_bf16 v[50:53], v[170:173], v[82:85], v[50:53]
	v_add_f32_e64 v84, v118, v120
	v_add_f32_e64 v85, v119, v121
	v_pk_add_f32 v[82:83], v[110:111], v[112:113]
	v_mfma_f32_16x16x32_bf16 v[50:53], v[162:165], v[86:89], v[50:53]
	v_add_f32_e64 v86, v114, v116
	v_add_f32_e64 v87, v115, v117
	v_pk_add_f32 v[84:85], v[84:85], v[86:87]
	v_mfma_f32_16x16x32_bf16 v[50:53], v[158:161], v[90:93], v[50:53]
	v_add_f32_e64 v86, v108, v98
	v_add_f32_e64 v87, v109, v99
	v_pk_add_f32 v[82:83], v[86:87], v[82:83]
	v_mfma_f32_16x16x32_bf16 v[50:53], v[154:157], v[94:97], v[50:53]
	v_add_f32_e64 v82, v82, v84
	v_add_f32_e64 v83, v83, v85
	v_add_f32_e32 v82, v82, v83
	ds_bpermute_b32 v83, v145, v82
	s_add_i32 s81, s81, -1
	s_mov_b64 s[60:61], 0
	s_waitcnt lgkmcnt(0)
	v_add_f32_e32 v82, v82, v83
	ds_bpermute_b32 v83, v146, v82
	s_waitcnt lgkmcnt(0)
	v_add_f32_e32 v82, v82, v83
	v_fmac_f32_e32 v82, v152, v0

.LBB0_293:
	s_cmp_eq_u32 s62, s97
	s_mov_b64 s[60:61], -1
	s_cbranch_scc1 .LBB0_286
	v_mov_b32_e32 v52, v124
	s_barrier
	s_movk_i32 s60, 0x110
	v_lshlrev_b32_e32 v0, 4, v52
	v_and_b32_e32 v0, 0xf0, v0
	v_add_u32_e32 v0, 0, v0
	v_lshrrev_b32_e32 v50, 4, v52
	v_mad_u64_u32 v[50:51], s[52:53], v50, s60, v[0:1]
	s_waitcnt vmcnt(3)
	ds_write_b128 v50, v[18:21]
	v_add_u32_e32 v50, 0x200, v52
	v_lshrrev_b32_e32 v50, 4, v50
	v_mad_u64_u32 v[50:51], s[52:53], v50, s60, v[0:1]
	s_waitcnt vmcnt(2)
	ds_write_b128 v50, v[22:25]
	v_add_u32_e32 v50, 0x400, v52
	v_lshrrev_b32_e32 v50, 4, v50
	v_mad_u64_u32 v[50:51], s[52:53], v50, s60, v[0:1]
	s_waitcnt vmcnt(1)
	ds_write_b128 v50, v[34:37]
	v_add_u32_e32 v50, 0x600, v52
	v_lshrrev_b32_e32 v50, 4, v50
	s_add_i32 s96, s97, 1
	v_mad_u64_u32 v[50:51], s[52:53], v50, s60, v[0:1]
	s_cmp_ge_u32 s96, s62
	s_waitcnt vmcnt(0)
	ds_write_b128 v50, v[38:41]
	s_waitcnt lgkmcnt(0)
	s_barrier
	s_and_b64 s[52:53], s[50:51], exec
	s_cselect_b32 s52, s97, s81
	s_lshl_b32 s52, s52, 7
	s_add_i32 s60, s52, s44
	v_add_u32_e32 v50, s60, v128
	v_ashrrev_i32_e32 v51, 31, v50
	v_lshlrev_b64 v[50:51], 6, v[50:51]
	v_mov_b32_e32 v102, v126
	v_lshl_add_u64 v[54:55], s[58:59], 0, v[50:51]
	global_load_dword v53, v[54:55], off offset:80
	global_load_dword v51, v[54:55], off offset:16
	global_load_dword v0, v[54:55], off offset:64
	global_load_dword v50, v[54:55], off
	s_mov_b32 s100, s60
	s_ashr_i32 s101, s60, 31
	s_lshl_b64 s[100:101], s[100:101], 1
	s_add_u32 s100, s93, s100
	s_addc_u32 s101, s94, s101
	global_load_dwordx4 v[180:183], v102, s[100:101]
	global_load_dwordx4 v[184:187], v102, s[100:101] offset:64
	global_load_dwordx4 v[188:191], v102, s[100:101] offset:128
	global_load_dwordx4 v[192:195], v102, s[100:101] offset:192
	s_cmp_ge_u32 s96, s62
	s_cbranch_scc1 .Lml1a_nopre
	v_mov_b32_e32 v175, 0
	s_add_i32 s100, s81, -1
	s_and_b64 s[52:53], s[50:51], exec
	s_cselect_b32 s52, s96, s100
	s_lshl_b32 s52, s52, 7
	s_ashr_i32 s53, s52, 31
	v_mov_b32_e32 v38, v124
	s_lshl_b64 s[52:53], s[52:53], 1
	s_add_u32 s52, s45, s52
	v_lshlrev_b32_e32 v174, 4, v38
	s_addc_u32 s53, s84, s53
	v_and_b32_e32 v174, 0xf0, v174
	v_lshl_add_u64 v[34:35], s[52:53], 0, v[174:175]
	v_ashrrev_i32_e32 v174, 4, v38
	s_movk_i32 s100, 0x6000
	v_mad_i64_i32 v[18:19], s[52:53], v174, s100, v[34:35]
	v_add_u32_e32 v174, 0x200, v38
	v_ashrrev_i32_e32 v174, 4, v174
	v_mad_i64_i32 v[22:23], s[52:53], v174, s100, v[34:35]
	v_add_u32_e32 v174, 0x400, v38
	v_ashrrev_i32_e32 v174, 4, v174
	v_mad_i64_i32 v[36:37], s[52:53], v174, s100, v[34:35]
	v_add_u32_e32 v174, 0x600, v38
	v_ashrrev_i32_e32 v174, 4, v174
	v_mad_i64_i32 v[38:39], s[52:53], v174, s100, v[34:35]
	global_load_dwordx4 v[18:21], v[18:19], off
	s_nop 0
	global_load_dwordx4 v[22:25], v[22:23], off
	s_nop 0
	global_load_dwordx4 v[34:37], v[36:37], off
	s_nop 0
	global_load_dwordx4 v[38:41], v[38:39], off
	s_branch .Lml1a_join
.Lml1a_nopre:
	global_load_dword v176, v[54:55], off
	global_load_dword v176, v[54:55], off
	global_load_dword v176, v[54:55], off
	global_load_dword v176, v[54:55], off
.Lml1a_join:
	s_andn2_b64 vcc, exec, s[48:49]
	s_mov_b64 s[52:53], -1
	s_waitcnt vmcnt(10)
	v_add_f32_e32 v52, v51, v53
	s_cbranch_vccnz .LBB0_298
	ds_bpermute_b32 v54, v129, v52
	s_mov_b64 s[52:53], 0
	s_waitcnt lgkmcnt(0)
	v_add_f32_e32 v54, v52, v54
	v_cndmask_b32_e64 v54, v52, v54, s[8:9]
	ds_bpermute_b32 v55, v130, v54
	s_waitcnt lgkmcnt(0)
	v_add_f32_e32 v55, v54, v55
	v_cndmask_b32_e64 v54, v54, v55, s[10:11]
	ds_bpermute_b32 v55, v131, v54
	s_waitcnt lgkmcnt(0)
	v_add_f32_e32 v55, v54, v55
	v_cndmask_b32_e64 v54, v54, v55, s[12:13]
	ds_bpermute_b32 v55, v132, v54
	s_waitcnt lgkmcnt(0)
	v_add_f32_e32 v55, v54, v55
	v_cndmask_b32_e64 v54, v54, v55, s[14:15]
	ds_bpermute_b32 v55, v133, v54
	s_waitcnt lgkmcnt(0)
	v_add_f32_e32 v55, v54, v55
	v_cndmask_b32_e64 v54, v54, v55, s[16:17]
	ds_bpermute_b32 v55, v134, v54
	s_waitcnt lgkmcnt(0)
	v_add_f32_e32 v55, v54, v55
	v_cndmask_b32_e64 v54, v54, v55, s[18:19]
	ds_bpermute_b32 v55, v129, v54
	v_readlane_b32 s61, v54, 0
	s_waitcnt lgkmcnt(0)
	v_cndmask_b32_e64 v55, v55, 0, s[20:21]
	v_add_f32_e32 v55, v53, v55

.LBB0_312:
	v_sub_f32_e32 v51, s61, v54
	s_waitcnt vmcnt(8)
	v_add_f32_e32 v50, v50, v51
	v_sub_f32_e32 v51, s61, v55
	v_add_f32_e32 v0, v0, v51
	v_max_f32_e32 v51, v50, v0
	ds_bpermute_b32 v52, v141, v51
	v_add_f32_e32 v53, s61, v151
	s_ashr_i32 s61, s60, 31
	s_lshl_b64 s[52:53], s[60:61], 1
	s_add_u32 s60, s3, s52
	s_waitcnt lgkmcnt(0)
	v_max_f32_e32 v52, v52, v52
	v_max_f32_e32 v51, v51, v52
	ds_bpermute_b32 v52, v142, v51
	s_addc_u32 s61, s85, s53
	s_waitcnt lgkmcnt(0)
	v_max_f32_e32 v52, v52, v52
	v_max_f32_e32 v51, v51, v52
	ds_bpermute_b32 v52, v143, v51
	s_waitcnt lgkmcnt(0)
	v_max_f32_e32 v52, v52, v52
	v_max_f32_e32 v51, v51, v52
	ds_bpermute_b32 v52, v144, v51
	s_waitcnt lgkmcnt(0)
	v_max_f32_e32 v52, v52, v52
	v_max_f32_e32 v51, v51, v52
	ds_bpermute_b32 v52, v145, v51
	s_waitcnt lgkmcnt(0)
	v_max_f32_e32 v52, v52, v52
	v_max_f32_e32 v51, v51, v52
	ds_bpermute_b32 v52, v146, v51
	s_waitcnt lgkmcnt(0)
	v_max3_f32 v153, v53, v51, v52
	v_sub_f32_e32 v50, v50, v153
	v_sub_f32_e32 v0, v0, v153
	v_mul_f32_e32 v50, 0x3fb8aa3b, v50
	v_mul_f32_e32 v0, 0x3fb8aa3b, v0
	v_exp_f32_e32 v50, v50
	v_exp_f32_e32 v51, v0
	v_sub_f32_e32 v0, v53, v153
	v_mul_f32_e32 v0, 0x3fb8aa3b, v0
	v_exp_f32_e32 v0, v0
	ds_write_b64 v147, v[50:51]
	ds_read_b128 v[82:85], v148
	ds_read_b128 v[86:89], v148 offset:16
	s_waitcnt vmcnt(7)
	v_mov_b32_e32 v90, v180
	v_mov_b32_e32 v91, v181
	v_mov_b32_e32 v92, v182
	v_mov_b32_e32 v93, v183
	v_pk_mul_f32 v[80:81], v[48:49], v[0:1] op_sel_hi:[1,0]
	v_pk_mul_f32 v[78:79], v[46:47], v[0:1] op_sel_hi:[1,0]
	v_pk_mul_f32 v[76:77], v[44:45], v[0:1] op_sel_hi:[1,0]
	v_pk_mul_f32 v[74:75], v[42:43], v[0:1] op_sel_hi:[1,0]
	v_pk_mul_f32 v[72:73], v[40:41], v[0:1] op_sel_hi:[1,0]
	v_pk_mul_f32 v[70:71], v[38:39], v[0:1] op_sel_hi:[1,0]
	v_pk_mul_f32 v[68:69], v[36:37], v[0:1] op_sel_hi:[1,0]
	v_pk_mul_f32 v[66:67], v[34:35], v[0:1] op_sel_hi:[1,0]
	v_pk_mul_f32 v[64:65], v[32:33], v[0:1] op_sel_hi:[1,0]
	v_pk_mul_f32 v[62:63], v[30:31], v[0:1] op_sel_hi:[1,0]
	v_pk_mul_f32 v[60:61], v[28:29], v[0:1] op_sel_hi:[1,0]
	v_pk_mul_f32 v[58:59], v[26:27], v[0:1] op_sel_hi:[1,0]
	v_pk_mul_f32 v[56:57], v[24:25], v[0:1] op_sel_hi:[1,0]
	v_pk_mul_f32 v[54:55], v[22:23], v[0:1] op_sel_hi:[1,0]
	v_pk_mul_f32 v[52:53], v[20:21], v[0:1] op_sel_hi:[1,0]
	v_pk_mul_f32 v[50:51], v[18:19], v[0:1] op_sel_hi:[1,0]
	s_waitcnt vmcnt(4)
	v_lshlrev_b32_e32 v94, 16, v90
	v_and_b32_e32 v95, 0xffff0000, v90
	v_lshlrev_b32_e32 v90, 16, v91
	v_and_b32_e32 v91, 0xffff0000, v91
	s_waitcnt lgkmcnt(1)
	v_pk_mul_f32 v[84:85], v[84:85], v[90:91]
	v_lshlrev_b32_e32 v90, 16, v92
	v_and_b32_e32 v91, 0xffff0000, v92
	v_pk_mul_f32 v[82:83], v[82:83], v[94:95]
	s_waitcnt lgkmcnt(0)
	v_pk_mul_f32 v[86:87], v[86:87], v[90:91]
	v_lshlrev_b32_e32 v90, 16, v93
	v_and_b32_e32 v91, 0xffff0000, v93
	v_pk_mul_f32 v[88:89], v[88:89], v[90:91]
	v_mov_b32_e32 v90, v82
	v_mov_b32_e32 v91, v86
	v_mov_b32_e32 v92, v83
	v_mov_b32_e32 v93, v87
	v_pk_add_f32 v[90:91], v[90:91], v[92:93]
	v_mov_b32_e32 v92, v84
	v_mov_b32_e32 v93, v88
	v_mov_b32_e32 v94, v85
	v_mov_b32_e32 v95, v89
	v_pk_add_f32 v[92:93], v[92:93], v[94:95]
	v_cvt_pk_bf16_f32 v82, v82, v83
	v_pk_add_f32 v[90:91], v[90:91], v[92:93]
	v_cvt_pk_bf16_f32 v83, v84, v85
	v_pk_add_f32 v[108:109], v[90:91], v[90:91] op_sel:[0,1] op_sel_hi:[1,0]
	v_cvt_pk_bf16_f32 v84, v86, v87
	v_cvt_pk_bf16_f32 v85, v88, v89
	ds_read_b128 v[86:89], v148 offset:128
	ds_read_b128 v[90:93], v148 offset:144
	s_waitcnt vmcnt(6)
	v_mov_b32_e32 v94, v184
	v_mov_b32_e32 v95, v185
	v_mov_b32_e32 v96, v186
	v_mov_b32_e32 v97, v187
	s_waitcnt vmcnt(4)
	v_lshlrev_b32_e32 v98, 16, v94
	v_and_b32_e32 v99, 0xffff0000, v94
	v_lshlrev_b32_e32 v94, 16, v95
	v_and_b32_e32 v95, 0xffff0000, v95
	s_waitcnt lgkmcnt(1)
	v_pk_mul_f32 v[88:89], v[88:89], v[94:95]
	v_lshlrev_b32_e32 v94, 16, v96
	v_and_b32_e32 v95, 0xffff0000, v96
	v_pk_mul_f32 v[86:87], v[86:87], v[98:99]
	s_waitcnt lgkmcnt(0)
	v_pk_mul_f32 v[90:91], v[90:91], v[94:95]
	v_lshlrev_b32_e32 v94, 16, v97
	v_and_b32_e32 v95, 0xffff0000, v97
	v_pk_mul_f32 v[92:93], v[92:93], v[94:95]
	v_mov_b32_e32 v94, v86
	v_mov_b32_e32 v95, v88
	v_mov_b32_e32 v96, v87
	v_mov_b32_e32 v97, v89
	v_pk_add_f32 v[94:95], v[94:95], v[96:97]
	v_mov_b32_e32 v96, v91
	v_pk_add_f32 v[110:111], v[94:95], v[94:95] op_sel:[0,1] op_sel_hi:[1,0]
	v_mov_b32_e32 v94, v90
	v_mov_b32_e32 v95, v92
	v_mov_b32_e32 v97, v93
	v_pk_add_f32 v[94:95], v[94:95], v[96:97]
	v_cvt_pk_bf16_f32 v86, v86, v87
	v_pk_add_f32 v[112:113], v[94:95], v[94:95] op_sel:[0,1] op_sel_hi:[1,0]
	v_cvt_pk_bf16_f32 v87, v88, v89
	v_cvt_pk_bf16_f32 v88, v90, v91
	v_cvt_pk_bf16_f32 v89, v92, v93
	ds_read_b128 v[94:97], v148 offset:256
	ds_read_b128 v[90:93], v148 offset:272
	s_waitcnt vmcnt(5)
	v_mov_b32_e32 v98, v188
	v_mov_b32_e32 v99, v189
	v_mov_b32_e32 v100, v190
	v_mov_b32_e32 v101, v191
	s_waitcnt vmcnt(4)
	v_lshlrev_b32_e32 v104, 16, v98
	v_and_b32_e32 v105, 0xffff0000, v98
	v_lshlrev_b32_e32 v98, 16, v99
	v_and_b32_e32 v99, 0xffff0000, v99
	v_lshlrev_b32_e32 v114, 16, v100
	v_and_b32_e32 v115, 0xffff0000, v100
	v_lshlrev_b32_e32 v100, 16, v101
	v_and_b32_e32 v101, 0xffff0000, v101
	s_waitcnt lgkmcnt(1)
	v_pk_mul_f32 v[122:123], v[94:95], v[104:105]
	v_pk_mul_f32 v[154:155], v[96:97], v[98:99]
	s_waitcnt lgkmcnt(0)
	v_pk_mul_f32 v[158:159], v[92:93], v[100:101]
	v_pk_fma_f32 v[118:119], v[94:95], v[104:105], v[122:123] op_sel:[0,0,1] op_sel_hi:[1,1,0]
	v_pk_fma_f32 v[120:121], v[96:97], v[98:99], v[154:155] op_sel:[0,0,1] op_sel_hi:[1,1,0]
	v_pk_fma_f32 v[116:117], v[92:93], v[100:101], v[158:159] op_sel:[0,0,1] op_sel_hi:[1,1,0]
	ds_read_b128 v[98:101], v148 offset:384
	ds_read_b128 v[94:97], v148 offset:400
	s_waitcnt vmcnt(4)
	v_mov_b32_e32 v102, v192
	v_mov_b32_e32 v103, v193
	v_mov_b32_e32 v104, v194
	v_mov_b32_e32 v105, v195
	v_pk_mul_f32 v[156:157], v[90:91], v[114:115]
	v_cvt_pk_bf16_f32 v93, v158, v159
	v_pk_fma_f32 v[114:115], v[90:91], v[114:115], v[156:157] op_sel:[0,0,1] op_sel_hi:[1,1,0]
	v_cvt_pk_bf16_f32 v90, v122, v123
	v_cvt_pk_bf16_f32 v91, v154, v155
	v_cvt_pk_bf16_f32 v92, v156, v157
	s_waitcnt vmcnt(4)
	v_lshlrev_b32_e32 v122, 16, v102
	v_and_b32_e32 v123, 0xffff0000, v102
	v_lshlrev_b32_e32 v102, 16, v103
	v_and_b32_e32 v103, 0xffff0000, v103
	s_waitcnt lgkmcnt(1)
	v_pk_mul_f32 v[98:99], v[98:99], v[122:123]
	v_pk_mul_f32 v[122:123], v[100:101], v[102:103]
	v_lshlrev_b32_e32 v100, 16, v104
	v_and_b32_e32 v101, 0xffff0000, v104
	s_waitcnt lgkmcnt(0)
	v_pk_mul_f32 v[102:103], v[94:95], v[100:101]
	v_lshlrev_b32_e32 v94, 16, v105
	v_and_b32_e32 v95, 0xffff0000, v105
	v_pk_mul_f32 v[100:101], v[96:97], v[94:95]
	v_cvt_pk_bf16_f32 v94, v98, v99
	v_cvt_pk_bf16_f32 v95, v122, v123
	v_cvt_pk_bf16_f32 v96, v102, v103
	v_cvt_pk_bf16_f32 v97, v100, v101
	ds_read_b128 v[154:157], v149
	s_waitcnt lgkmcnt(0)
	v_mfma_f32_16x16x32_bf16 v[78:81], v[154:157], v[82:85], v[78:81]
	ds_read_b128 v[154:157], v149 offset:4352
	s_waitcnt lgkmcnt(0)
	v_mfma_f32_16x16x32_bf16 v[154:157], v[154:157], v[82:85], v[74:77]
	s_nop 2
	ds_read_b128 v[74:77], v149 offset:64
	s_waitcnt lgkmcnt(0)
	v_mfma_f32_16x16x32_bf16 v[74:77], v[74:77], v[86:89], v[78:81]
	s_nop 2
	ds_read_b128 v[78:81], v149 offset:128
	s_waitcnt lgkmcnt(0)
	v_mfma_f32_16x16x32_bf16 v[74:77], v[78:81], v[90:93], v[74:77]
	ds_read_b128 v[78:81], v149 offset:192
	s_waitcnt lgkmcnt(0)
	v_mfma_f32_16x16x32_bf16 v[74:77], v[78:81], v[94:97], v[74:77]
	ds_read_b128 v[78:81], v149 offset:4416
	s_waitcnt lgkmcnt(0)
	v_mfma_f32_16x16x32_bf16 v[78:81], v[78:81], v[86:89], v[154:157]
	s_nop 2
	ds_read_b128 v[154:157], v149 offset:4480
	s_waitcnt lgkmcnt(0)
	v_mfma_f32_16x16x32_bf16 v[78:81], v[154:157], v[90:93], v[78:81]
	ds_read_b128 v[154:157], v149 offset:4544
	s_waitcnt lgkmcnt(0)
	v_mfma_f32_16x16x32_bf16 v[78:81], v[154:157], v[94:97], v[78:81]
	ds_read_b128 v[154:157], v149 offset:8704
	s_waitcnt lgkmcnt(0)
	v_mfma_f32_16x16x32_bf16 v[70:73], v[154:157], v[82:85], v[70:73]
	ds_read_b128 v[154:157], v149 offset:8768
	s_waitcnt lgkmcnt(0)
	v_mfma_f32_16x16x32_bf16 v[70:73], v[154:157], v[86:89], v[70:73]
	ds_read_b128 v[154:157], v149 offset:8832
	s_waitcnt lgkmcnt(0)
	v_mfma_f32_16x16x32_bf16 v[70:73], v[154:157], v[90:93], v[70:73]
	ds_read_b128 v[154:157], v149 offset:8896
	s_waitcnt lgkmcnt(0)
	v_mfma_f32_16x16x32_bf16 v[70:73], v[154:157], v[94:97], v[70:73]
	ds_read_b128 v[154:157], v149 offset:13056
	s_waitcnt lgkmcnt(0)
	v_mfma_f32_16x16x32_bf16 v[66:69], v[154:157], v[82:85], v[66:69]
	ds_read_b128 v[154:157], v149 offset:13120
	s_waitcnt lgkmcnt(0)
	v_mfma_f32_16x16x32_bf16 v[66:69], v[154:157], v[86:89], v[66:69]
	ds_read_b128 v[154:157], v149 offset:13184
	s_waitcnt lgkmcnt(0)
	v_mfma_f32_16x16x32_bf16 v[66:69], v[154:157], v[90:93], v[66:69]
	ds_read_b128 v[154:157], v149 offset:13248
	s_waitcnt lgkmcnt(0)
	v_mfma_f32_16x16x32_bf16 v[66:69], v[154:157], v[94:97], v[66:69]
	ds_read_b128 v[154:157], v149 offset:17408
	v_mov_b32_e32 v119, v102
	v_mov_b32_e32 v121, v103
	v_mov_b32_e32 v115, v100
	v_mov_b32_e32 v117, v101
	v_mov_b32_e32 v111, v122
	v_mov_b32_e32 v113, v123
	v_mov_b32_e32 v109, v98
	v_mov_b32_e32 v98, v1
	s_waitcnt lgkmcnt(0)
	v_mfma_f32_16x16x32_bf16 v[62:65], v[154:157], v[82:85], v[62:65]
	ds_read_b128 v[154:157], v149 offset:17472
	s_waitcnt lgkmcnt(0)
	v_mfma_f32_16x16x32_bf16 v[62:65], v[154:157], v[86:89], v[62:65]
	ds_read_b128 v[154:157], v149 offset:17536
	s_waitcnt lgkmcnt(0)
	v_mfma_f32_16x16x32_bf16 v[62:65], v[154:157], v[90:93], v[62:65]
	ds_read_b128 v[154:157], v149 offset:17600
	s_waitcnt lgkmcnt(0)
	v_mfma_f32_16x16x32_bf16 v[62:65], v[154:157], v[94:97], v[62:65]
	ds_read_b128 v[154:157], v149 offset:21952
	ds_read_b128 v[158:161], v149 offset:21888
	ds_read_b128 v[162:165], v149 offset:21824
	ds_read_b128 v[170:173], v149 offset:21760
	s_waitcnt lgkmcnt(0)
	v_mfma_f32_16x16x32_bf16 v[58:61], v[170:173], v[82:85], v[58:61]
	v_mfma_f32_16x16x32_bf16 v[58:61], v[162:165], v[86:89], v[58:61]
	v_mfma_f32_16x16x32_bf16 v[58:61], v[158:161], v[90:93], v[58:61]
	v_mfma_f32_16x16x32_bf16 v[58:61], v[154:157], v[94:97], v[58:61]
	ds_read_b128 v[154:157], v149 offset:26304
	ds_read_b128 v[158:161], v149 offset:26240
	ds_read_b128 v[162:165], v149 offset:26176
	ds_read_b128 v[170:173], v149 offset:26112
	s_waitcnt lgkmcnt(0)
	v_mfma_f32_16x16x32_bf16 v[54:57], v[170:173], v[82:85], v[54:57]
	v_mfma_f32_16x16x32_bf16 v[54:57], v[162:165], v[86:89], v[54:57]
	v_mfma_f32_16x16x32_bf16 v[54:57], v[158:161], v[90:93], v[54:57]
	v_mfma_f32_16x16x32_bf16 v[54:57], v[154:157], v[94:97], v[54:57]
	ds_read_b128 v[154:157], v149 offset:30656
	ds_read_b128 v[158:161], v149 offset:30592
	ds_read_b128 v[162:165], v149 offset:30528
	ds_read_b128 v[170:173], v149 offset:30464
	s_waitcnt lgkmcnt(0)
	v_mfma_f32_16x16x32_bf16 v[50:53], v[170:173], v[82:85], v[50:53]
	v_add_f32_e64 v84, v118, v120
	v_add_f32_e64 v85, v119, v121
	v_pk_add_f32 v[82:83], v[110:111], v[112:113]
	v_mfma_f32_16x16x32_bf16 v[50:53], v[162:165], v[86:89], v[50:53]
	v_add_f32_e64 v86, v114, v116
	v_add_f32_e64 v87, v115, v117
	v_pk_add_f32 v[84:85], v[84:85], v[86:87]
	v_mfma_f32_16x16x32_bf16 v[50:53], v[158:161], v[90:93], v[50:53]
	v_add_f32_e64 v86, v108, v98
	v_add_f32_e64 v87, v109, v99
	v_pk_add_f32 v[82:83], v[86:87], v[82:83]
	v_mfma_f32_16x16x32_bf16 v[50:53], v[154:157], v[94:97], v[50:53]
	v_add_f32_e64 v82, v82, v84
	v_add_f32_e64 v83, v83, v85
	v_add_f32_e32 v82, v82, v83
	ds_bpermute_b32 v83, v145, v82
	s_add_i32 s77, s77, -1
	s_add_i32 s84, s84, 1
	s_mov_b64 s[60:61], 0
	s_waitcnt lgkmcnt(0)
	v_add_f32_e32 v82, v82, v83
	ds_bpermute_b32 v83, v146, v82
	s_waitcnt lgkmcnt(0)
	v_add_f32_e32 v82, v82, v83
	v_fmac_f32_e32 v82, v152, v0

.LBB0_324:
	s_andn2_b64 vcc, exec, s[60:61]
	s_mov_b64 s[60:61], -1
	s_cbranch_vccnz .LBB0_313
	v_mov_b32_e32 v52, v124
	s_barrier
	s_movk_i32 s60, 0x110
	v_lshlrev_b32_e32 v0, 4, v52
	v_and_b32_e32 v0, 0xf0, v0
	v_add_u32_e32 v0, 0, v0
	v_lshrrev_b32_e32 v50, 4, v52
	v_mad_u64_u32 v[50:51], s[52:53], v50, s60, v[0:1]
	s_waitcnt vmcnt(3)
	ds_write_b128 v50, v[2:5]
	v_add_u32_e32 v50, 0x200, v52
	v_lshrrev_b32_e32 v50, 4, v50
	v_mad_u64_u32 v[50:51], s[52:53], v50, s60, v[0:1]
	s_waitcnt vmcnt(2)
	ds_write_b128 v50, v[6:9]
	v_add_u32_e32 v50, 0x400, v52
	v_lshrrev_b32_e32 v50, 4, v50
	v_mad_u64_u32 v[50:51], s[52:53], v50, s60, v[0:1]
	s_waitcnt vmcnt(1)
	ds_write_b128 v50, v[10:13]
	v_add_u32_e32 v50, 0x600, v52
	v_lshrrev_b32_e32 v50, 4, v50
	v_mad_u64_u32 v[50:51], s[52:53], v50, s60, v[0:1]
	s_cmp_lg_u32 s84, 0
	s_waitcnt vmcnt(0)
	ds_write_b128 v50, v[14:17]
	s_waitcnt lgkmcnt(0)
	s_barrier
	s_and_b64 s[52:53], s[40:41], exec
	s_cselect_b32 s52, s84, s77
	s_lshl_b32 s52, s52, 7
	s_add_i32 s60, s52, s80
	v_add_u32_e32 v50, s60, v128
	v_ashrrev_i32_e32 v51, 31, v50
	v_lshlrev_b64 v[50:51], 6, v[50:51]
	v_mov_b32_e32 v102, v126
	v_lshl_add_u64 v[54:55], s[48:49], 0, v[50:51]
	global_load_dword v53, v[54:55], off offset:80
	global_load_dword v51, v[54:55], off offset:16
	global_load_dword v0, v[54:55], off offset:64
	global_load_dword v50, v[54:55], off
	s_mov_b32 s100, s60
	s_ashr_i32 s101, s60, 31
	s_lshl_b64 s[100:101], s[100:101], 1
	s_add_u32 s100, s3, s100
	s_addc_u32 s101, s85, s101
	global_load_dwordx4 v[180:183], v102, s[100:101]
	global_load_dwordx4 v[184:187], v102, s[100:101] offset:64
	global_load_dwordx4 v[188:191], v102, s[100:101] offset:128
	global_load_dwordx4 v[192:195], v102, s[100:101] offset:192
	s_cmp_lg_u32 s84, 0
	s_cbranch_scc1 .Lml1b_nopre
	v_mov_b32_e32 v175, 0
	v_mov_b32_e32 v14, v124
	s_movk_i32 s100, 0x6000
	v_lshlrev_b32_e32 v174, 4, v14
	v_and_b32_e32 v174, 0xf0, v174
	v_lshl_add_u64 v[10:11], s[58:59], 0, v[174:175]
	v_ashrrev_i32_e32 v174, 4, v14
	v_mad_i64_i32 v[2:3], s[52:53], v174, s100, v[10:11]
	v_add_u32_e32 v174, 0x200, v14
	v_ashrrev_i32_e32 v174, 4, v174
	v_mad_i64_i32 v[6:7], s[52:53], v174, s100, v[10:11]
	v_add_u32_e32 v174, 0x400, v14
	v_ashrrev_i32_e32 v174, 4, v174
	v_mad_i64_i32 v[12:13], s[52:53], v174, s100, v[10:11]
	v_add_u32_e32 v174, 0x600, v14
	v_ashrrev_i32_e32 v174, 4, v174
	v_mad_i64_i32 v[14:15], s[52:53], v174, s100, v[10:11]
	global_load_dwordx4 v[2:5], v[2:3], off
	s_nop 0
	global_load_dwordx4 v[6:9], v[6:7], off
	s_nop 0
	global_load_dwordx4 v[10:13], v[12:13], off
	s_nop 0
	global_load_dwordx4 v[14:17], v[14:15], off
	s_branch .Lml1b_join

.Lml1b_join:
	s_andn2_b64 vcc, exec, s[42:43]
	s_mov_b64 s[52:53], -1
	s_waitcnt vmcnt(10)
	v_add_f32_e32 v52, v51, v53
	s_cbranch_vccnz .LBB0_329
	ds_bpermute_b32 v54, v129, v52
	s_mov_b64 s[52:53], 0
	s_waitcnt lgkmcnt(0)
	v_add_f32_e32 v54, v52, v54
	v_cndmask_b32_e64 v54, v52, v54, s[8:9]
	ds_bpermute_b32 v55, v130, v54
	s_waitcnt lgkmcnt(0)
	v_add_f32_e32 v55, v54, v55
	v_cndmask_b32_e64 v54, v54, v55, s[10:11]
	ds_bpermute_b32 v55, v131, v54
	s_waitcnt lgkmcnt(0)
	v_add_f32_e32 v55, v54, v55
	v_cndmask_b32_e64 v54, v54, v55, s[12:13]
	ds_bpermute_b32 v55, v132, v54
	s_waitcnt lgkmcnt(0)
	v_add_f32_e32 v55, v54, v55
	v_cndmask_b32_e64 v54, v54, v55, s[14:15]
	ds_bpermute_b32 v55, v133, v54
	s_waitcnt lgkmcnt(0)
	v_add_f32_e32 v55, v54, v55
	v_cndmask_b32_e64 v54, v54, v55, s[16:17]
	ds_bpermute_b32 v55, v134, v54
	s_waitcnt lgkmcnt(0)
	v_add_f32_e32 v55, v54, v55
	v_cndmask_b32_e64 v54, v54, v55, s[18:19]
	ds_bpermute_b32 v55, v129, v54
	v_readlane_b32 s61, v54, 0
	s_waitcnt lgkmcnt(0)
	v_cndmask_b32_e64 v55, v55, 0, s[20:21]
	v_add_f32_e32 v55, v53, v55

.LBB0_798:
	s_waitcnt vmcnt(0)
	v_readlane_b32 s76, v254, 39
	v_readlane_b32 s84, v254, 46
	v_readlane_b32 s94, v254, 52
	v_readlane_b32 s56, v254, 54
	v_readlane_b32 s18, v254, 61
	v_readlane_b32 s58, v255, 22
	v_readlane_b32 s60, v255, 14
	v_readlane_b32 s68, v255, 32
	v_readlane_b32 s70, v255, 34
	v_readlane_b32 s66, v254, 38
	v_readlane_b32 s77, v254, 40
	v_readlane_b32 s78, v254, 41
	v_readlane_b32 s92, v254, 43
	s_movk_i32 s93, 0x80
	v_readlane_b32 s96, v254, 44
	v_readlane_b32 s85, v254, 47
	v_readlane_b32 s95, v254, 53
	v_readlane_b32 s57, v254, 55
	v_readlane_b32 s29, v254, 56
	v_readlane_b32 s35, v254, 57
	v_readlane_b32 s38, v254, 58
	s_mov_b32 s39, 0x12000
	s_movk_i32 s40, 0x3000
	s_mov_b32 s41, 0x18000
	s_mov_b32 s42, 0x9000
	s_movk_i32 s43, 0xffe0
	s_mov_b32 s44, 0x28000
	s_mov_b32 s45, 0x7f800000
	s_mov_b64 s[50:51], 0x48000
	v_readlane_b32 s19, v254, 62
	v_readlane_b32 s59, v255, 23
	v_readlane_b32 s61, v255, 15
	v_readlane_b32 s67, v255, 26
	v_readlane_b32 s80, v255, 29
	v_readlane_b32 s69, v255, 33
	v_readlane_b32 s71, v255, 35
	s_barrier
	v_readlane_b32 s0, v255, 0
	s_cmp_lg_u32 s0, 0
	s_cbranch_scc1 .Lfz_nosig
	v_readlane_b32 s0, v255, 11
	s_cmp_eq_u32 s0, 4
	s_cselect_b32 s1, 1, 0
	s_cmp_eq_u32 s0, 8
	s_cselect_b32 s1, 1, s1
	s_cmp_eq_u32 s1, 0
	s_cbranch_scc1 .Lfz_nosig
	s_cmpk_gt_i32 s67, 191
	s_cbranch_scc1 .Lfz_nosig
	v_readlane_b32 s0, v254, 63
	s_cmp_lg_u32 s0, 0
	s_cbranch_scc1 .Lfz_nosig
	s_and_b32 s0, s67, 7
	s_mul_i32 s0, s0, 6
	s_lshr_b32 s1, s67, 3
	s_mul_i32 s2, s1, 43
	s_lshr_b32 s2, s2, 8
	s_mul_i32 s3, s2, 6
	s_sub_i32 s1, s1, s3
	s_add_i32 s0, s0, s1
	s_lshl_b32 s0, s0, 2
	s_lshl_b32 s1, s18, 8
	s_add_i32 s0, s0, s1
	s_add_i32 s0, s0, 0x10000
	v_readlane_b32 s2, v255, 7
	v_readlane_b32 s3, v255, 8
	s_add_u32 s2, s2, s0
	s_addc_u32 s3, s3, 0
	s_mov_b64 s[0:1], exec
	s_mov_b64 exec, 1
	global_atomic_add v1, v226, s[2:3]
	s_mov_b64 exec, s[0:1]
.Lfz_nosig:
	v_readlane_b32 s79, v254, 42
	v_readlane_b32 s97, v254, 45

.LBB0_899:
	s_andn2_b64 vcc, exec, s[68:69]
	s_cbranch_vccnz .LBB0_1130
	v_readlane_b32 s0, v255, 11
	s_cmp_gt_i32 s0, 0
	s_mov_b64 s[2:3], -1
	s_cbranch_scc0 .LBB0_1013
	s_mov_b32 s0, s67
	s_mov_b32 s79, s0
	s_lshl_b32 s1, s0, 3
	v_readlane_b32 s0, v254, 63
	v_writelane_b32 v255, s58, 22
	s_add_i32 s1, s1, s0
	s_mov_b32 s67, 0x7f800000
	v_writelane_b32 v255, s59, 23
	v_mov_b32_e32 v0, v1
	s_cmpk_gt_i32 s1, 0x7ff
	s_cbranch_scc1 .LBB0_1012
	s_mov_b32 s100, s80
	s_ashr_i32 s0, s80, 2
	s_and_b32 s8, s80, 3
	s_cmp_eq_u32 s80, 1
	v_readlane_b32 s10, v255, 14
	s_cselect_b64 s[56:57], -1, 0
	s_or_b32 s2, s8, s0
	v_readlane_b32 s11, v255, 15
	s_cmp_lg_u32 s2, 0
	s_load_dwordx2 s[2:3], s[10:11], 0x58
	s_mul_i32 s0, s0, 3
	s_cselect_b64 s[94:95], -1, 0
	s_add_i32 s6, s0, s8
	s_ashr_i32 s7, s6, 31
	s_lshl_b64 s[6:7], s[6:7], 12
	s_waitcnt lgkmcnt(0)
	s_add_u32 s2, s2, s6
	s_addc_u32 s3, s3, s7
	v_mbcnt_lo_u32_b32 v0, -1, v0
	s_add_u32 s70, s10, 8
	v_mbcnt_hi_u32_b32 v92, -1, v0
	s_addc_u32 s71, s11, 0
	s_mulk_i32 s8, 0x3000
	v_readlane_b32 s6, v255, 22
	s_mul_i32 s80, s1, 6
	v_lshlrev_b32_e32 v94, 3, v92
	s_add_u32 s1, s6, s8
	v_ashrrev_i32_e32 v93, 31, v92
	v_readlane_b32 s8, v255, 5
	v_ashrrev_i32_e32 v95, 31, v94
	s_waitcnt vmcnt(0)
	v_lshlrev_b64 v[4:5], 2, v[92:93]
	v_readlane_b32 s10, v255, 7
	v_readlane_b32 s11, v255, 8
	v_lshl_add_u64 v[100:101], v[94:95], 2, s[2:3]
	v_lshlrev_b64 v[102:103], 5, v[94:95]
	v_lshl_add_u64 v[6:7], s[10:11], 0, v[4:5]
	s_mov_b64 s[10:11], 0x200000
	s_mov_b64 s[2:3], 0x4000
	v_readlane_b32 s7, v255, 23
	v_lshl_add_u64 v[98:99], v[6:7], 0, s[10:11]
	v_or_b32_e32 v6, 4, v94
	v_lshl_add_u64 v[104:105], v[102:103], 0, s[2:3]
	s_mov_b64 s[2:3], 0x4040
	s_addc_u32 s54, s7, 0
	v_ashrrev_i32_e32 v7, 31, v6
	v_lshl_add_u64 v[114:115], v[102:103], 0, s[2:3]
	s_mov_b64 s[2:3], 0x40c0
	s_ashr_i32 s81, s80, 31
	v_readlane_b32 s6, v255, 9
	v_lshlrev_b32_e32 v0, 2, v92
	v_add_u32_e32 v106, 0x204, v94
	v_or_b32_e32 v8, 2, v94
	v_lshlrev_b64 v[110:111], 5, v[6:7]
	v_or_b32_e32 v6, 6, v94
	v_lshl_add_u64 v[118:119], v[102:103], 0, s[2:3]
	s_lshl_b64 s[2:3], s[80:81], 6
	v_lshlrev_b64 v[2:3], 1, v[94:95]
	v_readlane_b32 s7, v255, 10
	v_xor_b32_e32 v126, 4, v0
	v_xor_b32_e32 v127, 8, v0
	v_xor_b32_e32 v128, 16, v0
	v_xor_b32_e32 v129, 32, v0
	v_xor_b32_e32 v130, 64, v0
	v_xor_b32_e32 v131, 0x80, v0
	v_and_b32_e32 v0, 4, v92
	v_ashrrev_i32_e32 v107, 31, v106
	v_ashrrev_i32_e32 v9, 31, v8
	v_ashrrev_i32_e32 v7, 31, v6
	v_lshl_add_u64 v[120:121], s[2:3], 0, v[4:5]
	s_lshl_b64 s[2:3], s[80:81], 11
	v_lshl_add_u64 v[96:97], s[6:7], 0, v[2:3]
	v_cmp_gt_i32_e64 s[6:7], 16, v92
	v_cmp_ne_u32_e64 s[74:75], 0, v0
	v_lshlrev_b64 v[108:109], 5, v[8:9]
	v_lshlrev_b64 v[112:113], 5, v[6:7]
	v_lshlrev_b64 v[116:117], 5, v[106:107]
	v_cmp_eq_u32_e64 s[68:69], 15, v92
	v_cmp_eq_u32_e64 s[12:13], 14, v92
	v_cmp_eq_u32_e64 s[14:15], 13, v92
	v_cmp_eq_u32_e64 s[16:17], 12, v92
	v_cmp_eq_u32_e64 s[18:19], 11, v92
	v_cmp_eq_u32_e64 s[20:21], 10, v92
	v_cmp_eq_u32_e64 s[22:23], 9, v92
	v_cmp_eq_u32_e64 s[24:25], 8, v92
	v_cmp_eq_u32_e64 s[26:27], 7, v92
	v_cmp_eq_u32_e64 s[28:29], 6, v92
	v_cmp_eq_u32_e64 s[30:31], 5, v92
	v_cmp_eq_u32_e64 s[34:35], 4, v92
	v_cmp_eq_u32_e64 s[36:37], 3, v92
	v_cmp_eq_u32_e64 s[38:39], 2, v92
	v_cmp_eq_u32_e64 s[40:41], 1, v92
	v_cmp_eq_u32_e64 s[42:43], 0, v92
	v_lshl_add_u64 v[122:123], s[2:3], 0, v[2:3]
	v_readlane_b32 s9, v255, 6
	s_cmp_lt_u32 s100, 2
	s_cbranch_scc1 .Lfn_old
	s_cmp_eq_u32 s100, 4
	s_cbranch_scc1 .Lfn_old
	s_cmpk_gt_i32 s79, 191
	s_cbranch_scc1 .LBB0_1012
	s_and_b32 s0, s79, 7
	s_mul_i32 s0, s0, 6
	s_lshr_b32 s1, s79, 3
	s_mul_i32 s2, s1, 43
	s_lshr_b32 s2, s2, 8
	s_mul_i32 s3, s2, 6
	s_sub_i32 s1, s1, s3
	s_add_i32 s0, s0, s1
	s_lshl_b32 s80, s0, 8
	s_lshl_b32 s2, s2, 6
	s_add_i32 s80, s80, s2
	v_readlane_b32 s3, v254, 63
	s_lshl_b32 s2, s3, 3
	s_add_i32 s80, s80, s2
	s_mov_b32 s81, 0
	v_readlane_b32 s1, v254, 61
	s_add_i32 s1, s1, -1
	s_lshl_b32 s1, s1, 8
	s_lshl_b32 s0, s0, 2
	s_add_i32 s0, s0, s1
	s_add_i32 s0, s0, 0x10000
	v_readlane_b32 s22, v255, 7
	v_readlane_b32 s23, v255, 8
	s_add_u32 s22, s22, s0
	s_addc_u32 s23, s23, 0
	s_sub_i32 s1, s80, 0x1800
	s_max_i32 s1, s1, 0
	s_lshr_b32 s1, s1, 11
	s_ashr_i32 s0, s100, 2
	s_and_b32 s6, s100, 3
	s_mul_i32 s7, s0, 3
	s_add_i32 s8, s7, s6
	v_readlane_b32 s10, v255, 14
	v_readlane_b32 s11, v255, 15
	s_load_dwordx2 s[12:13], s[10:11], 0x58
	s_add_i32 s9, s7, s1
	s_mul_i32 s9, s9, 0x9000
	s_mul_i32 s14, s6, 0x3000
	s_add_i32 s9, s9, s14
	s_add_i32 s9, s9, 0x100000
	v_readlane_b32 s20, v255, 7
	v_readlane_b32 s21, v255, 8
	s_add_u32 s20, s20, s9
	s_addc_u32 s21, s21, 0
	v_lshlrev_b32_e32 v82, 5, v92
	v_lshlrev_b32_e32 v83, 4, v92
	s_lshl_b32 s8, s8, 12
	s_add_u32 s26, s20, 0x1000
	s_addc_u32 s27, s21, 0
	s_waitcnt lgkmcnt(0)
	s_add_u32 s12, s12, s8
	s_addc_u32 s13, s13, 0
	global_load_dwordx4 v[148:151], v82, s[12:13] offset:0
	global_load_dwordx4 v[170:173], v82, s[26:27] offset:0
	global_load_dwordx4 v[186:189], v82, s[20:21] offset:0
	global_load_dwordx4 v[152:155], v82, s[12:13] offset:16
	global_load_dwordx4 v[174:177], v82, s[26:27] offset:16
	global_load_dwordx4 v[190:193], v82, s[20:21] offset:16
	global_load_dwordx4 v[156:159], v82, s[12:13] offset:2048
	global_load_dwordx4 v[178:181], v82, s[26:27] offset:2048
	global_load_dwordx4 v[194:197], v82, s[20:21] offset:2048
	global_load_dwordx4 v[160:163], v82, s[12:13] offset:2064
	global_load_dwordx4 v[182:185], v82, s[26:27] offset:2064
	global_load_dwordx4 v[198:201], v82, s[20:21] offset:2064
	s_cmp_lg_u32 s3, 0
	s_cbranch_scc1 .Lfn_bar
	s_mov_b32 s2, 0
.Lfn_poll:
	global_load_dword v84, v1, s[22:23] sc1
	s_waitcnt vmcnt(0)
	v_readfirstlane_b32 s0, v84
	s_cmp_ge_u32 s0, 4
	s_cbranch_scc1 .Lfn_ok
	s_add_i32 s2, s2, 1
	s_cmp_gt_u32 s2, 0x20000
	s_cbranch_scc1 .Lfn_ok
	s_sleep 1
	s_branch .Lfn_poll

.Lfn_bar:
	s_barrier
	v_readlane_b32 s24, v255, 5
	v_readlane_b32 s25, v255, 6
	s_lshl_b64 s[26:27], s[80:81], 12
	s_add_u32 s24, s24, s26
	s_addc_u32 s25, s25, s27
	global_load_dwordx4 v[2:5], v82, s[24:25] offset:0
	global_load_dwordx4 v[6:9], v82, s[24:25] offset:16
	global_load_dwordx4 v[10:13], v82, s[24:25] offset:2048
	global_load_dwordx4 v[14:17], v82, s[24:25] offset:2064
	s_add_u32 s24, s24, 0x1000
	s_addc_u32 s25, s25, 0
	global_load_dwordx4 v[18:21], v82, s[24:25] offset:0
	global_load_dwordx4 v[22:25], v82, s[24:25] offset:16
	global_load_dwordx4 v[26:29], v82, s[24:25] offset:2048
	global_load_dwordx4 v[30:33], v82, s[24:25] offset:2064
	s_add_u32 s24, s24, 0x1000
	s_addc_u32 s25, s25, 0
	global_load_dwordx4 v[34:37], v82, s[24:25] offset:0
	global_load_dwordx4 v[38:41], v82, s[24:25] offset:16
	global_load_dwordx4 v[42:45], v82, s[24:25] offset:2048
	global_load_dwordx4 v[46:49], v82, s[24:25] offset:2064
	s_add_u32 s24, s24, 0x1000
	s_addc_u32 s25, s25, 0
	global_load_dwordx4 v[50:53], v82, s[24:25] offset:0
	global_load_dwordx4 v[54:57], v82, s[24:25] offset:16
	global_load_dwordx4 v[58:61], v82, s[24:25] offset:2048
	global_load_dwordx4 v[62:65], v82, s[24:25] offset:2064
	s_add_u32 s24, s24, 0x1000
	s_addc_u32 s25, s25, 0
	global_load_dwordx4 v[66:69], v82, s[24:25] offset:0
	global_load_dwordx4 v[70:73], v82, s[24:25] offset:16
	global_load_dwordx4 v[74:77], v82, s[24:25] offset:2048
	global_load_dwordx4 v[78:81], v82, s[24:25] offset:2064
	s_add_u32 s24, s24, 0x1000
	s_addc_u32 s25, s25, 0
	global_load_dwordx4 v[132:135], v82, s[24:25] offset:0
	global_load_dwordx4 v[136:139], v82, s[24:25] offset:16
	global_load_dwordx4 v[140:143], v82, s[24:25] offset:2048
	global_load_dwordx4 v[144:147], v82, s[24:25] offset:2064
	s_add_u32 s24, s24, 0x1000
	s_addc_u32 s25, s25, 0
	global_load_dwordx4 v[94:97], v82, s[24:25] offset:0
	global_load_dwordx4 v[98:101], v82, s[24:25] offset:16
	global_load_dwordx4 v[102:105], v82, s[24:25] offset:2048
	global_load_dwordx4 v[106:109], v82, s[24:25] offset:2064
	s_add_u32 s24, s24, 0x1000
	s_addc_u32 s25, s25, 0
	global_load_dwordx4 v[110:113], v82, s[24:25] offset:0
	global_load_dwordx4 v[114:117], v82, s[24:25] offset:16
	global_load_dwordx4 v[118:121], v82, s[24:25] offset:2048
	global_load_dwordx4 v[122:125], v82, s[24:25] offset:2064
	s_mov_b32 s28, 0x3a800000
	s_waitcnt vmcnt(32)
	v_add_f32_e32 v170, 1.0, v170
	v_add_f32_e32 v171, 1.0, v171
	v_add_f32_e32 v172, 1.0, v172
	v_add_f32_e32 v173, 1.0, v173
	v_add_f32_e32 v174, 1.0, v174
	v_add_f32_e32 v175, 1.0, v175
	v_add_f32_e32 v176, 1.0, v176
	v_add_f32_e32 v177, 1.0, v177
	v_add_f32_e32 v178, 1.0, v178
	v_add_f32_e32 v179, 1.0, v179
	v_add_f32_e32 v180, 1.0, v180
	v_add_f32_e32 v181, 1.0, v181
	v_add_f32_e32 v182, 1.0, v182
	v_add_f32_e32 v183, 1.0, v183
	v_add_f32_e32 v184, 1.0, v184
	v_add_f32_e32 v185, 1.0, v185
	v_mul_f32_e32 v170, v148, v170
	v_mul_f32_e32 v171, v149, v171
	v_mul_f32_e32 v172, v150, v172
	v_mul_f32_e32 v173, v151, v173
	v_mul_f32_e32 v174, v152, v174
	v_mul_f32_e32 v175, v153, v175
	v_mul_f32_e32 v176, v154, v176
	v_mul_f32_e32 v177, v155, v177
	v_mul_f32_e32 v178, v156, v178
	v_mul_f32_e32 v179, v157, v179
	v_mul_f32_e32 v180, v158, v180
	v_mul_f32_e32 v181, v159, v181
	v_mul_f32_e32 v182, v160, v182
	v_mul_f32_e32 v183, v161, v183
	v_mul_f32_e32 v184, v162, v184
	v_mul_f32_e32 v185, v163, v185
	s_waitcnt vmcnt(28)
	v_mul_f32_e32 v202, v2, v2
	v_fmac_f32_e32 v202, v3, v3
	v_fmac_f32_e32 v202, v4, v4
	v_fmac_f32_e32 v202, v5, v5
	v_fmac_f32_e32 v202, v6, v6
	v_fmac_f32_e32 v202, v7, v7
	v_fmac_f32_e32 v202, v8, v8
	v_fmac_f32_e32 v202, v9, v9
	v_fmac_f32_e32 v202, v10, v10
	v_fmac_f32_e32 v202, v11, v11
	v_fmac_f32_e32 v202, v12, v12
	v_fmac_f32_e32 v202, v13, v13
	v_fmac_f32_e32 v202, v14, v14
	v_fmac_f32_e32 v202, v15, v15
	v_fmac_f32_e32 v202, v16, v16
	v_fmac_f32_e32 v202, v17, v17
	s_waitcnt vmcnt(24)
	v_mul_f32_e32 v203, v18, v18
	v_fmac_f32_e32 v203, v19, v19
	v_fmac_f32_e32 v203, v20, v20
	v_fmac_f32_e32 v203, v21, v21
	v_fmac_f32_e32 v203, v22, v22
	v_fmac_f32_e32 v203, v23, v23
	v_fmac_f32_e32 v203, v24, v24
	v_fmac_f32_e32 v203, v25, v25
	v_fmac_f32_e32 v203, v26, v26
	v_fmac_f32_e32 v203, v27, v27
	v_fmac_f32_e32 v203, v28, v28
	v_fmac_f32_e32 v203, v29, v29
	v_fmac_f32_e32 v203, v30, v30
	v_fmac_f32_e32 v203, v31, v31
	v_fmac_f32_e32 v203, v32, v32
	v_fmac_f32_e32 v203, v33, v33
	s_waitcnt vmcnt(20)
	v_mul_f32_e32 v204, v34, v34
	v_fmac_f32_e32 v204, v35, v35
	v_fmac_f32_e32 v204, v36, v36
	v_fmac_f32_e32 v204, v37, v37
	v_fmac_f32_e32 v204, v38, v38
	v_fmac_f32_e32 v204, v39, v39
	v_fmac_f32_e32 v204, v40, v40
	v_fmac_f32_e32 v204, v41, v41
	v_fmac_f32_e32 v204, v42, v42
	v_fmac_f32_e32 v204, v43, v43
	v_fmac_f32_e32 v204, v44, v44
	v_fmac_f32_e32 v204, v45, v45
	v_fmac_f32_e32 v204, v46, v46
	v_fmac_f32_e32 v204, v47, v47
	v_fmac_f32_e32 v204, v48, v48
	v_fmac_f32_e32 v204, v49, v49
	s_waitcnt vmcnt(16)
	v_mul_f32_e32 v205, v50, v50
	v_fmac_f32_e32 v205, v51, v51
	v_fmac_f32_e32 v205, v52, v52
	v_fmac_f32_e32 v205, v53, v53
	v_fmac_f32_e32 v205, v54, v54
	v_fmac_f32_e32 v205, v55, v55
	v_fmac_f32_e32 v205, v56, v56
	v_fmac_f32_e32 v205, v57, v57
	v_fmac_f32_e32 v205, v58, v58
	v_fmac_f32_e32 v205, v59, v59
	v_fmac_f32_e32 v205, v60, v60
	v_fmac_f32_e32 v205, v61, v61
	v_fmac_f32_e32 v205, v62, v62
	v_fmac_f32_e32 v205, v63, v63
	v_fmac_f32_e32 v205, v64, v64
	v_fmac_f32_e32 v205, v65, v65
	s_waitcnt vmcnt(12)
	v_mul_f32_e32 v206, v66, v66
	v_fmac_f32_e32 v206, v67, v67
	v_fmac_f32_e32 v206, v68, v68
	v_fmac_f32_e32 v206, v69, v69
	v_fmac_f32_e32 v206, v70, v70
	v_fmac_f32_e32 v206, v71, v71
	v_fmac_f32_e32 v206, v72, v72
	v_fmac_f32_e32 v206, v73, v73
	v_fmac_f32_e32 v206, v74, v74
	v_fmac_f32_e32 v206, v75, v75
	v_fmac_f32_e32 v206, v76, v76
	v_fmac_f32_e32 v206, v77, v77
	v_fmac_f32_e32 v206, v78, v78
	v_fmac_f32_e32 v206, v79, v79
	v_fmac_f32_e32 v206, v80, v80
	v_fmac_f32_e32 v206, v81, v81
	s_waitcnt vmcnt(8)
	v_mul_f32_e32 v207, v132, v132
	v_fmac_f32_e32 v207, v133, v133
	v_fmac_f32_e32 v207, v134, v134
	v_fmac_f32_e32 v207, v135, v135
	v_fmac_f32_e32 v207, v136, v136
	v_fmac_f32_e32 v207, v137, v137
	v_fmac_f32_e32 v207, v138, v138
	v_fmac_f32_e32 v207, v139, v139
	v_fmac_f32_e32 v207, v140, v140
	v_fmac_f32_e32 v207, v141, v141
	v_fmac_f32_e32 v207, v142, v142
	v_fmac_f32_e32 v207, v143, v143
	v_fmac_f32_e32 v207, v144, v144
	v_fmac_f32_e32 v207, v145, v145
	v_fmac_f32_e32 v207, v146, v146
	v_fmac_f32_e32 v207, v147, v147
	s_waitcnt vmcnt(4)
	v_mul_f32_e32 v208, v94, v94
	v_fmac_f32_e32 v208, v95, v95
	v_fmac_f32_e32 v208, v96, v96
	v_fmac_f32_e32 v208, v97, v97
	v_fmac_f32_e32 v208, v98, v98
	v_fmac_f32_e32 v208, v99, v99
	v_fmac_f32_e32 v208, v100, v100
	v_fmac_f32_e32 v208, v101, v101
	v_fmac_f32_e32 v208, v102, v102
	v_fmac_f32_e32 v208, v103, v103
	v_fmac_f32_e32 v208, v104, v104
	v_fmac_f32_e32 v208, v105, v105
	v_fmac_f32_e32 v208, v106, v106
	v_fmac_f32_e32 v208, v107, v107
	v_fmac_f32_e32 v208, v108, v108
	v_fmac_f32_e32 v208, v109, v109
	s_waitcnt vmcnt(0)
	v_mul_f32_e32 v209, v110, v110
	v_fmac_f32_e32 v209, v111, v111
	v_fmac_f32_e32 v209, v112, v112
	v_fmac_f32_e32 v209, v113, v113
	v_fmac_f32_e32 v209, v114, v114
	v_fmac_f32_e32 v209, v115, v115
	v_fmac_f32_e32 v209, v116, v116
	v_fmac_f32_e32 v209, v117, v117
	v_fmac_f32_e32 v209, v118, v118
	v_fmac_f32_e32 v209, v119, v119
	v_fmac_f32_e32 v209, v120, v120
	v_fmac_f32_e32 v209, v121, v121
	v_fmac_f32_e32 v209, v122, v122
	v_fmac_f32_e32 v209, v123, v123
	v_fmac_f32_e32 v209, v124, v124
	v_fmac_f32_e32 v209, v125, v125
	s_nop 1
	v_add_f32_dpp v202, v202, v202 row_ror:8 row_mask:0xf bank_mask:0xf
	v_add_f32_dpp v203, v203, v203 row_ror:8 row_mask:0xf bank_mask:0xf
	v_add_f32_dpp v204, v204, v204 row_ror:8 row_mask:0xf bank_mask:0xf
	v_add_f32_dpp v205, v205, v205 row_ror:8 row_mask:0xf bank_mask:0xf
	v_add_f32_dpp v206, v206, v206 row_ror:8 row_mask:0xf bank_mask:0xf
	v_add_f32_dpp v207, v207, v207 row_ror:8 row_mask:0xf bank_mask:0xf
	v_add_f32_dpp v208, v208, v208 row_ror:8 row_mask:0xf bank_mask:0xf
	v_add_f32_dpp v209, v209, v209 row_ror:8 row_mask:0xf bank_mask:0xf
	v_add_f32_dpp v202, v202, v202 row_ror:4 row_mask:0xf bank_mask:0xf
	v_add_f32_dpp v203, v203, v203 row_ror:4 row_mask:0xf bank_mask:0xf
	v_add_f32_dpp v204, v204, v204 row_ror:4 row_mask:0xf bank_mask:0xf
	v_add_f32_dpp v205, v205, v205 row_ror:4 row_mask:0xf bank_mask:0xf
	v_add_f32_dpp v206, v206, v206 row_ror:4 row_mask:0xf bank_mask:0xf
	v_add_f32_dpp v207, v207, v207 row_ror:4 row_mask:0xf bank_mask:0xf
	v_add_f32_dpp v208, v208, v208 row_ror:4 row_mask:0xf bank_mask:0xf
	v_add_f32_dpp v209, v209, v209 row_ror:4 row_mask:0xf bank_mask:0xf
	v_add_f32_dpp v202, v202, v202 row_ror:2 row_mask:0xf bank_mask:0xf
	v_add_f32_dpp v203, v203, v203 row_ror:2 row_mask:0xf bank_mask:0xf
	v_add_f32_dpp v204, v204, v204 row_ror:2 row_mask:0xf bank_mask:0xf
	v_add_f32_dpp v205, v205, v205 row_ror:2 row_mask:0xf bank_mask:0xf
	v_add_f32_dpp v206, v206, v206 row_ror:2 row_mask:0xf bank_mask:0xf
	v_add_f32_dpp v207, v207, v207 row_ror:2 row_mask:0xf bank_mask:0xf
	v_add_f32_dpp v208, v208, v208 row_ror:2 row_mask:0xf bank_mask:0xf
	v_add_f32_dpp v209, v209, v209 row_ror:2 row_mask:0xf bank_mask:0xf
	v_add_f32_dpp v202, v202, v202 row_ror:1 row_mask:0xf bank_mask:0xf
	v_add_f32_dpp v203, v203, v203 row_ror:1 row_mask:0xf bank_mask:0xf
	v_add_f32_dpp v204, v204, v204 row_ror:1 row_mask:0xf bank_mask:0xf
	v_add_f32_dpp v205, v205, v205 row_ror:1 row_mask:0xf bank_mask:0xf
	v_add_f32_dpp v206, v206, v206 row_ror:1 row_mask:0xf bank_mask:0xf
	v_add_f32_dpp v207, v207, v207 row_ror:1 row_mask:0xf bank_mask:0xf
	v_add_f32_dpp v208, v208, v208 row_ror:1 row_mask:0xf bank_mask:0xf
	v_add_f32_dpp v209, v209, v209 row_ror:1 row_mask:0xf bank_mask:0xf
	v_mov_b32_e32 v210, v202
	v_mov_b32_e32 v211, v203
	v_mov_b32_e32 v212, v204
	v_mov_b32_e32 v213, v205
	v_mov_b32_e32 v214, v206
	v_mov_b32_e32 v215, v207
	v_mov_b32_e32 v216, v208
	v_mov_b32_e32 v217, v209
	s_nop 1
	v_permlane16_swap_b32_e32 v210, v202
	v_permlane16_swap_b32_e32 v211, v203
	v_permlane16_swap_b32_e32 v212, v204
	v_permlane16_swap_b32_e32 v213, v205
	v_permlane16_swap_b32_e32 v214, v206
	v_permlane16_swap_b32_e32 v215, v207
	v_permlane16_swap_b32_e32 v216, v208
	v_permlane16_swap_b32_e32 v217, v209
	v_add_f32_e32 v202, v202, v210
	v_add_f32_e32 v203, v203, v211
	v_add_f32_e32 v204, v204, v212
	v_add_f32_e32 v205, v205, v213
	v_add_f32_e32 v206, v206, v214
	v_add_f32_e32 v207, v207, v215
	v_add_f32_e32 v208, v208, v216
	v_add_f32_e32 v209, v209, v217
	v_mov_b32_e32 v210, v202
	v_mov_b32_e32 v211, v203
	v_mov_b32_e32 v212, v204
	v_mov_b32_e32 v213, v205
	v_mov_b32_e32 v214, v206
	v_mov_b32_e32 v215, v207
	v_mov_b32_e32 v216, v208
	v_mov_b32_e32 v217, v209
	s_nop 1
	v_permlane32_swap_b32_e32 v210, v202
	v_permlane32_swap_b32_e32 v211, v203
	v_permlane32_swap_b32_e32 v212, v204
	v_permlane32_swap_b32_e32 v213, v205
	v_permlane32_swap_b32_e32 v214, v206
	v_permlane32_swap_b32_e32 v215, v207
	v_permlane32_swap_b32_e32 v216, v208
	v_permlane32_swap_b32_e32 v217, v209
	v_add_f32_e32 v202, v202, v210
	v_add_f32_e32 v203, v203, v211
	v_add_f32_e32 v204, v204, v212
	v_add_f32_e32 v205, v205, v213
	v_add_f32_e32 v206, v206, v214
	v_add_f32_e32 v207, v207, v215
	v_add_f32_e32 v208, v208, v216
	v_add_f32_e32 v209, v209, v217
	v_fma_f32 v202, v202, s28, v167
	v_fma_f32 v203, v203, s28, v167
	v_fma_f32 v204, v204, s28, v167
	v_fma_f32 v205, v205, s28, v167
	v_fma_f32 v206, v206, s28, v167
	v_fma_f32 v207, v207, s28, v167
	v_fma_f32 v208, v208, s28, v167
	v_fma_f32 v209, v209, s28, v167
	v_rsq_f32_e32 v202, v202
	v_rsq_f32_e32 v203, v203
	v_rsq_f32_e32 v204, v204
	v_rsq_f32_e32 v205, v205
	v_rsq_f32_e32 v206, v206
	v_rsq_f32_e32 v207, v207
	v_rsq_f32_e32 v208, v208
	v_rsq_f32_e32 v209, v209
	s_nop 0
	v_mul_f32_e32 v2, v2, v202
	v_mul_f32_e32 v3, v3, v202
	v_mul_f32_e32 v4, v4, v202
	v_mul_f32_e32 v5, v5, v202
	v_mul_f32_e32 v6, v6, v202
	v_mul_f32_e32 v7, v7, v202
	v_mul_f32_e32 v8, v8, v202
	v_mul_f32_e32 v9, v9, v202
	v_mul_f32_e32 v10, v10, v202
	v_mul_f32_e32 v11, v11, v202
	v_mul_f32_e32 v12, v12, v202
	v_mul_f32_e32 v13, v13, v202
	v_mul_f32_e32 v14, v14, v202
	v_mul_f32_e32 v15, v15, v202
	v_mul_f32_e32 v16, v16, v202
	v_mul_f32_e32 v17, v17, v202
	v_fma_f32 v2, v2, v170, v186
	v_fma_f32 v3, v3, v171, v187
	v_fma_f32 v4, v4, v172, v188
	v_fma_f32 v5, v5, v173, v189
	v_fma_f32 v6, v6, v174, v190
	v_fma_f32 v7, v7, v175, v191
	v_fma_f32 v8, v8, v176, v192
	v_fma_f32 v9, v9, v177, v193
	v_fma_f32 v10, v10, v178, v194
	v_fma_f32 v11, v11, v179, v195
	v_fma_f32 v12, v12, v180, v196
	v_fma_f32 v13, v13, v181, v197
	v_fma_f32 v14, v14, v182, v198
	v_fma_f32 v15, v15, v183, v199
	v_fma_f32 v16, v16, v184, v200
	v_fma_f32 v17, v17, v185, v201
	v_mul_f32_e32 v18, v18, v203
	v_mul_f32_e32 v19, v19, v203
	v_mul_f32_e32 v20, v20, v203
	v_mul_f32_e32 v21, v21, v203
	v_mul_f32_e32 v22, v22, v203
	v_mul_f32_e32 v23, v23, v203
	v_mul_f32_e32 v24, v24, v203
	v_mul_f32_e32 v25, v25, v203
	v_mul_f32_e32 v26, v26, v203
	v_mul_f32_e32 v27, v27, v203
	v_mul_f32_e32 v28, v28, v203
	v_mul_f32_e32 v29, v29, v203
	v_mul_f32_e32 v30, v30, v203
	v_mul_f32_e32 v31, v31, v203
	v_mul_f32_e32 v32, v32, v203
	v_mul_f32_e32 v33, v33, v203
	v_fma_f32 v18, v18, v170, v186
	v_fma_f32 v19, v19, v171, v187
	v_fma_f32 v20, v20, v172, v188
	v_fma_f32 v21, v21, v173, v189
	v_fma_f32 v22, v22, v174, v190
	v_fma_f32 v23, v23, v175, v191
	v_fma_f32 v24, v24, v176, v192
	v_fma_f32 v25, v25, v177, v193
	v_fma_f32 v26, v26, v178, v194
	v_fma_f32 v27, v27, v179, v195
	v_fma_f32 v28, v28, v180, v196
	v_fma_f32 v29, v29, v181, v197
	v_fma_f32 v30, v30, v182, v198
	v_fma_f32 v31, v31, v183, v199
	v_fma_f32 v32, v32, v184, v200
	v_fma_f32 v33, v33, v185, v201
	v_mul_f32_e32 v34, v34, v204
	v_mul_f32_e32 v35, v35, v204
	v_mul_f32_e32 v36, v36, v204
	v_mul_f32_e32 v37, v37, v204
	v_mul_f32_e32 v38, v38, v204
	v_mul_f32_e32 v39, v39, v204
	v_mul_f32_e32 v40, v40, v204
	v_mul_f32_e32 v41, v41, v204
	v_mul_f32_e32 v42, v42, v204
	v_mul_f32_e32 v43, v43, v204
	v_mul_f32_e32 v44, v44, v204
	v_mul_f32_e32 v45, v45, v204
	v_mul_f32_e32 v46, v46, v204
	v_mul_f32_e32 v47, v47, v204
	v_mul_f32_e32 v48, v48, v204
	v_mul_f32_e32 v49, v49, v204
	v_fma_f32 v34, v34, v170, v186
	v_fma_f32 v35, v35, v171, v187
	v_fma_f32 v36, v36, v172, v188
	v_fma_f32 v37, v37, v173, v189
	v_fma_f32 v38, v38, v174, v190
	v_fma_f32 v39, v39, v175, v191
	v_fma_f32 v40, v40, v176, v192
	v_fma_f32 v41, v41, v177, v193
	v_fma_f32 v42, v42, v178, v194
	v_fma_f32 v43, v43, v179, v195
	v_fma_f32 v44, v44, v180, v196
	v_fma_f32 v45, v45, v181, v197
	v_fma_f32 v46, v46, v182, v198
	v_fma_f32 v47, v47, v183, v199
	v_fma_f32 v48, v48, v184, v200
	v_fma_f32 v49, v49, v185, v201
	v_mul_f32_e32 v50, v50, v205
	v_mul_f32_e32 v51, v51, v205
	v_mul_f32_e32 v52, v52, v205
	v_mul_f32_e32 v53, v53, v205
	v_mul_f32_e32 v54, v54, v205
	v_mul_f32_e32 v55, v55, v205
	v_mul_f32_e32 v56, v56, v205
	v_mul_f32_e32 v57, v57, v205
	v_mul_f32_e32 v58, v58, v205
	v_mul_f32_e32 v59, v59, v205
	v_mul_f32_e32 v60, v60, v205
	v_mul_f32_e32 v61, v61, v205
	v_mul_f32_e32 v62, v62, v205
	v_mul_f32_e32 v63, v63, v205
	v_mul_f32_e32 v64, v64, v205
	v_mul_f32_e32 v65, v65, v205
	v_fma_f32 v50, v50, v170, v186
	v_fma_f32 v51, v51, v171, v187
	v_fma_f32 v52, v52, v172, v188
	v_fma_f32 v53, v53, v173, v189
	v_fma_f32 v54, v54, v174, v190
	v_fma_f32 v55, v55, v175, v191
	v_fma_f32 v56, v56, v176, v192
	v_fma_f32 v57, v57, v177, v193
	v_fma_f32 v58, v58, v178, v194
	v_fma_f32 v59, v59, v179, v195
	v_fma_f32 v60, v60, v180, v196
	v_fma_f32 v61, v61, v181, v197
	v_fma_f32 v62, v62, v182, v198
	v_fma_f32 v63, v63, v183, v199
	v_fma_f32 v64, v64, v184, v200
	v_fma_f32 v65, v65, v185, v201
	v_mul_f32_e32 v66, v66, v206
	v_mul_f32_e32 v67, v67, v206
	v_mul_f32_e32 v68, v68, v206
	v_mul_f32_e32 v69, v69, v206
	v_mul_f32_e32 v70, v70, v206
	v_mul_f32_e32 v71, v71, v206
	v_mul_f32_e32 v72, v72, v206
	v_mul_f32_e32 v73, v73, v206
	v_mul_f32_e32 v74, v74, v206
	v_mul_f32_e32 v75, v75, v206
	v_mul_f32_e32 v76, v76, v206
	v_mul_f32_e32 v77, v77, v206
	v_mul_f32_e32 v78, v78, v206
	v_mul_f32_e32 v79, v79, v206
	v_mul_f32_e32 v80, v80, v206
	v_mul_f32_e32 v81, v81, v206
	v_fma_f32 v66, v66, v170, v186
	v_fma_f32 v67, v67, v171, v187
	v_fma_f32 v68, v68, v172, v188
	v_fma_f32 v69, v69, v173, v189
	v_fma_f32 v70, v70, v174, v190
	v_fma_f32 v71, v71, v175, v191
	v_fma_f32 v72, v72, v176, v192
	v_fma_f32 v73, v73, v177, v193
	v_fma_f32 v74, v74, v178, v194
	v_fma_f32 v75, v75, v179, v195
	v_fma_f32 v76, v76, v180, v196
	v_fma_f32 v77, v77, v181, v197
	v_fma_f32 v78, v78, v182, v198
	v_fma_f32 v79, v79, v183, v199
	v_fma_f32 v80, v80, v184, v200
	v_fma_f32 v81, v81, v185, v201
	v_mul_f32_e32 v132, v132, v207
	v_mul_f32_e32 v133, v133, v207
	v_mul_f32_e32 v134, v134, v207
	v_mul_f32_e32 v135, v135, v207
	v_mul_f32_e32 v136, v136, v207
	v_mul_f32_e32 v137, v137, v207
	v_mul_f32_e32 v138, v138, v207
	v_mul_f32_e32 v139, v139, v207
	v_mul_f32_e32 v140, v140, v207
	v_mul_f32_e32 v141, v141, v207
	v_mul_f32_e32 v142, v142, v207
	v_mul_f32_e32 v143, v143, v207
	v_mul_f32_e32 v144, v144, v207
	v_mul_f32_e32 v145, v145, v207
	v_mul_f32_e32 v146, v146, v207
	v_mul_f32_e32 v147, v147, v207
	v_fma_f32 v132, v132, v170, v186
	v_fma_f32 v133, v133, v171, v187
	v_fma_f32 v134, v134, v172, v188
	v_fma_f32 v135, v135, v173, v189
	v_fma_f32 v136, v136, v174, v190
	v_fma_f32 v137, v137, v175, v191
	v_fma_f32 v138, v138, v176, v192
	v_fma_f32 v139, v139, v177, v193
	v_fma_f32 v140, v140, v178, v194
	v_fma_f32 v141, v141, v179, v195
	v_fma_f32 v142, v142, v180, v196
	v_fma_f32 v143, v143, v181, v197
	v_fma_f32 v144, v144, v182, v198
	v_fma_f32 v145, v145, v183, v199
	v_fma_f32 v146, v146, v184, v200
	v_fma_f32 v147, v147, v185, v201
	v_mul_f32_e32 v94, v94, v208
	v_mul_f32_e32 v95, v95, v208
	v_mul_f32_e32 v96, v96, v208
	v_mul_f32_e32 v97, v97, v208
	v_mul_f32_e32 v98, v98, v208
	v_mul_f32_e32 v99, v99, v208
	v_mul_f32_e32 v100, v100, v208
	v_mul_f32_e32 v101, v101, v208
	v_mul_f32_e32 v102, v102, v208
	v_mul_f32_e32 v103, v103, v208
	v_mul_f32_e32 v104, v104, v208
	v_mul_f32_e32 v105, v105, v208
	v_mul_f32_e32 v106, v106, v208
	v_mul_f32_e32 v107, v107, v208
	v_mul_f32_e32 v108, v108, v208
	v_mul_f32_e32 v109, v109, v208
	v_fma_f32 v94, v94, v170, v186
	v_fma_f32 v95, v95, v171, v187
	v_fma_f32 v96, v96, v172, v188
	v_fma_f32 v97, v97, v173, v189
	v_fma_f32 v98, v98, v174, v190
	v_fma_f32 v99, v99, v175, v191
	v_fma_f32 v100, v100, v176, v192
	v_fma_f32 v101, v101, v177, v193
	v_fma_f32 v102, v102, v178, v194
	v_fma_f32 v103, v103, v179, v195
	v_fma_f32 v104, v104, v180, v196
	v_fma_f32 v105, v105, v181, v197
	v_fma_f32 v106, v106, v182, v198
	v_fma_f32 v107, v107, v183, v199
	v_fma_f32 v108, v108, v184, v200
	v_fma_f32 v109, v109, v185, v201
	v_mul_f32_e32 v110, v110, v209
	v_mul_f32_e32 v111, v111, v209
	v_mul_f32_e32 v112, v112, v209
	v_mul_f32_e32 v113, v113, v209
	v_mul_f32_e32 v114, v114, v209
	v_mul_f32_e32 v115, v115, v209
	v_mul_f32_e32 v116, v116, v209
	v_mul_f32_e32 v117, v117, v209
	v_mul_f32_e32 v118, v118, v209
	v_mul_f32_e32 v119, v119, v209
	v_mul_f32_e32 v120, v120, v209
	v_mul_f32_e32 v121, v121, v209
	v_mul_f32_e32 v122, v122, v209
	v_mul_f32_e32 v123, v123, v209
	v_mul_f32_e32 v124, v124, v209
	v_mul_f32_e32 v125, v125, v209
	v_fma_f32 v110, v110, v170, v186
	v_fma_f32 v111, v111, v171, v187
	v_fma_f32 v112, v112, v172, v188
	v_fma_f32 v113, v113, v173, v189
	v_fma_f32 v114, v114, v174, v190
	v_fma_f32 v115, v115, v175, v191
	v_fma_f32 v116, v116, v176, v192
	v_fma_f32 v117, v117, v177, v193
	v_fma_f32 v118, v118, v178, v194
	v_fma_f32 v119, v119, v179, v195
	v_fma_f32 v120, v120, v180, v196
	v_fma_f32 v121, v121, v181, v197
	v_fma_f32 v122, v122, v182, v198
	v_fma_f32 v123, v123, v183, v199
	v_fma_f32 v124, v124, v184, v200
	v_fma_f32 v125, v125, v185, v201
	v_readlane_b32 s24, v255, 9
	v_readlane_b32 s25, v255, 10
	s_lshl_b64 s[22:23], s[80:81], 11
	s_add_u32 s24, s24, s22
	s_addc_u32 s25, s25, s23
	v_cvt_pk_bf16_f32 v2, v2, v3
	v_cvt_pk_bf16_f32 v3, v4, v5
	v_cvt_pk_bf16_f32 v4, v6, v7
	v_cvt_pk_bf16_f32 v5, v8, v9
	v_cvt_pk_bf16_f32 v10, v10, v11
	v_cvt_pk_bf16_f32 v11, v12, v13
	v_cvt_pk_bf16_f32 v12, v14, v15
	v_cvt_pk_bf16_f32 v13, v16, v17
	global_store_dwordx4 v83, v[2:5], s[24:25]
	global_store_dwordx4 v83, v[10:13], s[24:25] offset:1024
	s_add_u32 s24, s24, 0x800
	s_addc_u32 s25, s25, 0
	v_cvt_pk_bf16_f32 v18, v18, v19
	v_cvt_pk_bf16_f32 v19, v20, v21
	v_cvt_pk_bf16_f32 v20, v22, v23
	v_cvt_pk_bf16_f32 v21, v24, v25
	v_cvt_pk_bf16_f32 v26, v26, v27
	v_cvt_pk_bf16_f32 v27, v28, v29
	v_cvt_pk_bf16_f32 v28, v30, v31
	v_cvt_pk_bf16_f32 v29, v32, v33
	global_store_dwordx4 v83, v[18:21], s[24:25]
	global_store_dwordx4 v83, v[26:29], s[24:25] offset:1024
	s_add_u32 s24, s24, 0x800
	s_addc_u32 s25, s25, 0
	v_cvt_pk_bf16_f32 v34, v34, v35
	v_cvt_pk_bf16_f32 v35, v36, v37
	v_cvt_pk_bf16_f32 v36, v38, v39
	v_cvt_pk_bf16_f32 v37, v40, v41
	v_cvt_pk_bf16_f32 v42, v42, v43
	v_cvt_pk_bf16_f32 v43, v44, v45
	v_cvt_pk_bf16_f32 v44, v46, v47
	v_cvt_pk_bf16_f32 v45, v48, v49
	global_store_dwordx4 v83, v[34:37], s[24:25]
	global_store_dwordx4 v83, v[42:45], s[24:25] offset:1024
	s_add_u32 s24, s24, 0x800
	s_addc_u32 s25, s25, 0
	v_cvt_pk_bf16_f32 v50, v50, v51
	v_cvt_pk_bf16_f32 v51, v52, v53
	v_cvt_pk_bf16_f32 v52, v54, v55
	v_cvt_pk_bf16_f32 v53, v56, v57
	v_cvt_pk_bf16_f32 v58, v58, v59
	v_cvt_pk_bf16_f32 v59, v60, v61
	v_cvt_pk_bf16_f32 v60, v62, v63
	v_cvt_pk_bf16_f32 v61, v64, v65
	global_store_dwordx4 v83, v[50:53], s[24:25]
	global_store_dwordx4 v83, v[58:61], s[24:25] offset:1024
	s_add_u32 s24, s24, 0x800
	s_addc_u32 s25, s25, 0
	v_cvt_pk_bf16_f32 v66, v66, v67
	v_cvt_pk_bf16_f32 v67, v68, v69
	v_cvt_pk_bf16_f32 v68, v70, v71
	v_cvt_pk_bf16_f32 v69, v72, v73
	v_cvt_pk_bf16_f32 v74, v74, v75
	v_cvt_pk_bf16_f32 v75, v76, v77
	v_cvt_pk_bf16_f32 v76, v78, v79
	v_cvt_pk_bf16_f32 v77, v80, v81
	global_store_dwordx4 v83, v[66:69], s[24:25]
	global_store_dwordx4 v83, v[74:77], s[24:25] offset:1024
	s_add_u32 s24, s24, 0x800
	s_addc_u32 s25, s25, 0
	v_cvt_pk_bf16_f32 v132, v132, v133
	v_cvt_pk_bf16_f32 v133, v134, v135
	v_cvt_pk_bf16_f32 v134, v136, v137
	v_cvt_pk_bf16_f32 v135, v138, v139
	v_cvt_pk_bf16_f32 v140, v140, v141
	v_cvt_pk_bf16_f32 v141, v142, v143
	v_cvt_pk_bf16_f32 v142, v144, v145
	v_cvt_pk_bf16_f32 v143, v146, v147
	global_store_dwordx4 v83, v[132:135], s[24:25]
	global_store_dwordx4 v83, v[140:143], s[24:25] offset:1024
	s_add_u32 s24, s24, 0x800
	s_addc_u32 s25, s25, 0
	v_cvt_pk_bf16_f32 v94, v94, v95
	v_cvt_pk_bf16_f32 v95, v96, v97
	v_cvt_pk_bf16_f32 v96, v98, v99
	v_cvt_pk_bf16_f32 v97, v100, v101
	v_cvt_pk_bf16_f32 v102, v102, v103
	v_cvt_pk_bf16_f32 v103, v104, v105
	v_cvt_pk_bf16_f32 v104, v106, v107
	v_cvt_pk_bf16_f32 v105, v108, v109
	global_store_dwordx4 v83, v[94:97], s[24:25]
	global_store_dwordx4 v83, v[102:105], s[24:25] offset:1024
	s_add_u32 s24, s24, 0x800
	s_addc_u32 s25, s25, 0
	v_cvt_pk_bf16_f32 v110, v110, v111
	v_cvt_pk_bf16_f32 v111, v112, v113
	v_cvt_pk_bf16_f32 v112, v114, v115
	v_cvt_pk_bf16_f32 v113, v116, v117
	v_cvt_pk_bf16_f32 v118, v118, v119
	v_cvt_pk_bf16_f32 v119, v120, v121
	v_cvt_pk_bf16_f32 v120, v122, v123
	v_cvt_pk_bf16_f32 v121, v124, v125
	global_store_dwordx4 v83, v[110:113], s[24:25]
	global_store_dwordx4 v83, v[118:121], s[24:25] offset:1024
	s_branch .LBB0_1012
.Lfn_old:
	s_sub_i32 s1, s80, 0x1800
	s_max_i32 s1, s1, 0
	s_lshr_b32 s1, s1, 11
	s_sub_i32 s3, s80, 0x17fb
	s_max_i32 s3, s3, 0
	s_lshr_b32 s3, s3, 11
	s_mov_b32 s2, 6
	s_cmp_eq_u32 s1, s3
	s_cbranch_scc1 .Lnrm_n0
	s_lshl_b32 s2, s3, 11
	s_add_i32 s2, s2, 0x1800
	s_sub_i32 s2, s2, s80

PROG:
	.byte	0, 0, 1
	.byte	1, 0, 1
	.byte	3, 0, 1
	.byte	4, 0, 1
	.byte	1, 1, 1
	.byte	5, 0, 1
	.byte	6, 0, 1
	.byte	7, 0, 1
	.byte	8, 0, 0
	.byte	1, 2, 1
	.byte	3, 1, 1
	.byte	4, 1, 1
	.byte	1, 4, 1
	.byte	3, 2, 1
	.byte	4, 2, 1
	.byte	2, 5, 1
	.byte	9, 0, 0
	.byte	10, 0, 1
	.byte	11, 0, 1
	.byte	8, 1, 0
	.byte	1, 6, 1
	.byte	3, 3, 1
	.byte	4, 3, 0
	.byte	1, 8, 1
	.byte	3, 4, 1
	.byte	4, 4, 0
	.byte	1, 9, 1
	.byte	12, 0, 1
	.byte	13, 0, 1
	.byte	14, 0, 1
	.byte	8, 2, 0
	.byte	1, 10, 1
	.byte	3, 5, 1
	.byte	4, 5, 0
	.byte	1, 12, 1
	.byte	3, 6, 1
	.byte	4, 6, 0
	.byte	1, 13, 1
	.byte	15, 0, 1
	.byte	16, 0, 1
	.byte	8, 3, 0
	.byte	1, 14, 1
	.byte	3, 7, 1
	.byte	4, 7, 1
	.byte	17, 0, 0
	.size	PROG, 135

	.protected	BGTAB
	.type	BGTAB,@object
	.globl	BGTAB
	.p2align	4, 0x0
